# hg_out prefetch v2: loop's own row-address chain shifted 16 tokens feeds the prefetch loads (96 fewer 64-bit adds per chunk)
# baseline (speedup 1.0000x reference)
.LBB0_686:
	s_ashr_i32 s24, s69, 9
	s_and_b32 s70, s67, 0x3f80
	s_ashr_i32 s25, s24, 31
	s_or_b32 s71, s70, 0x7f
	s_lshl_b64 s[56:57], s[24:25], 14
	s_mul_hi_i32 s3, s24, 0x3800000
	s_mul_i32 s24, s24, 0x3800000
	s_add_u32 s24, s50, s24
	s_addc_u32 s3, s51, s3
	s_lshl_b32 s54, s55, 1
	s_add_u32 s24, s24, s54
	s_addc_u32 s25, s3, 0
	s_lshl_b32 s3, s69, 1
	s_or_b32 s28, s3, s59
	v_ashrrev_i32_e32 v76, 4, v0
	s_ashr_i32 s29, s28, 31
	v_lshlrev_b32_e32 v77, 2, v76
	s_lshl_b64 s[28:29], s[28:29], 14
	v_and_b32_e32 v3, 15, v0
	v_lshlrev_b32_e32 v1, 8, v76
	v_or_b32_e32 v78, 1, v77
	s_add_u32 s28, s60, s28
	v_or_b32_e32 v4, v1, v3
	v_lshlrev_b32_e32 v22, 6, v78
	v_or_b32_e32 v24, 0x80, v1
	v_or_b32_e32 v26, 0xc0, v1
	s_addc_u32 s29, s61, s29
	v_ashrrev_i32_e32 v5, 31, v4
	v_or_b32_e32 v8, v22, v3
	v_or_b32_e32 v12, v24, v3
	v_or_b32_e32 v16, v26, v3
	v_lshl_add_u64 v[6:7], v[4:5], 2, s[28:29]
	v_ashrrev_i32_e32 v9, 31, v8
	v_ashrrev_i32_e32 v13, 31, v12
	v_ashrrev_i32_e32 v17, 31, v16
	v_ashrrev_i32_e32 v5, 31, v1
	v_lshl_add_u64 v[10:11], v[8:9], 2, s[28:29]
	v_lshl_add_u64 v[14:15], v[12:13], 2, s[28:29]
	v_lshl_add_u64 v[18:19], v[16:17], 2, s[28:29]
	v_lshl_add_u64 v[20:21], v[4:5], 2, s[28:29]
	v_ashrrev_i32_e32 v9, 31, v22
	v_ashrrev_i32_e32 v13, 31, v24
	v_ashrrev_i32_e32 v17, 31, v26
	v_add_u32_e32 v36, 0x400, v1
	v_lshl_add_u64 v[22:23], v[8:9], 2, s[28:29]
	v_lshl_add_u64 v[24:25], v[12:13], 2, s[28:29]
	v_lshl_add_u64 v[26:27], v[16:17], 2, s[28:29]
	global_load_dword v4, v[6:7], off
	global_load_dword v5, v[10:11], off
	s_nop 0
	global_load_dword v6, v[14:15], off
	global_load_dword v7, v[18:19], off
	global_load_dword v8, v[20:21], off offset:64
	global_load_dword v9, v[22:23], off offset:64
	global_load_dword v12, v[20:21], off offset:128
	global_load_dword v16, v[20:21], off offset:192
	global_load_dword v10, v[24:25], off offset:64
	global_load_dword v11, v[26:27], off offset:64
	global_load_dword v13, v[22:23], off offset:128
	global_load_dword v14, v[24:25], off offset:128
	global_load_dword v15, v[26:27], off offset:128
	global_load_dword v19, v[26:27], off offset:192
	global_load_dword v18, v[24:25], off offset:192
	global_load_dword v17, v[22:23], off offset:192
	v_or_b32_e32 v20, v36, v3
	v_add_u32_e32 v38, 0x440, v1
	v_add_u32_e32 v40, 0x480, v1
	v_add_u32_e32 v42, 0x4c0, v1
	v_ashrrev_i32_e32 v21, 31, v20
	v_or_b32_e32 v24, v38, v3
	v_or_b32_e32 v28, v40, v3
	v_or_b32_e32 v32, v42, v3
	v_lshl_add_u64 v[22:23], v[20:21], 2, s[28:29]
	v_ashrrev_i32_e32 v25, 31, v24
	v_ashrrev_i32_e32 v29, 31, v28
	v_ashrrev_i32_e32 v33, 31, v32
	v_ashrrev_i32_e32 v21, 31, v36
	v_lshl_add_u64 v[26:27], v[24:25], 2, s[28:29]
	v_lshl_add_u64 v[30:31], v[28:29], 2, s[28:29]
	v_lshl_add_u64 v[34:35], v[32:33], 2, s[28:29]
	v_lshl_add_u64 v[36:37], v[20:21], 2, s[28:29]
	v_ashrrev_i32_e32 v25, 31, v38
	v_ashrrev_i32_e32 v29, 31, v40
	v_ashrrev_i32_e32 v33, 31, v42
	v_add_u32_e32 v52, 0x800, v1
	v_add_u32_e32 v56, 0x880, v1
	v_lshl_add_u64 v[38:39], v[24:25], 2, s[28:29]
	v_lshl_add_u64 v[40:41], v[28:29], 2, s[28:29]
	v_lshl_add_u64 v[42:43], v[32:33], 2, s[28:29]
	global_load_dword v20, v[22:23], off
	global_load_dword v21, v[26:27], off
	s_nop 0
	global_load_dword v22, v[30:31], off
	global_load_dword v23, v[34:35], off
	global_load_dword v24, v[36:37], off offset:64
	global_load_dword v25, v[38:39], off offset:64
	global_load_dword v28, v[36:37], off offset:128
	global_load_dword v32, v[36:37], off offset:192
	global_load_dword v26, v[40:41], off offset:64
	global_load_dword v27, v[42:43], off offset:64
	global_load_dword v29, v[38:39], off offset:128
	global_load_dword v30, v[40:41], off offset:128
	global_load_dword v31, v[42:43], off offset:128
	global_load_dword v35, v[42:43], off offset:192
	global_load_dword v34, v[40:41], off offset:192
	global_load_dword v33, v[38:39], off offset:192
	v_or_b32_e32 v36, v52, v3
	v_add_u32_e32 v54, 0x840, v1
	v_or_b32_e32 v44, v56, v3
	v_add_u32_e32 v58, 0x8c0, v1
	v_ashrrev_i32_e32 v37, 31, v36
	v_or_b32_e32 v40, v54, v3
	v_ashrrev_i32_e32 v45, 31, v44
	v_or_b32_e32 v48, v58, v3
	v_lshl_add_u64 v[38:39], v[36:37], 2, s[28:29]
	v_ashrrev_i32_e32 v41, 31, v40
	v_lshl_add_u64 v[46:47], v[44:45], 2, s[28:29]
	v_ashrrev_i32_e32 v49, 31, v48
	v_ashrrev_i32_e32 v37, 31, v52
	v_ashrrev_i32_e32 v45, 31, v56
	v_lshl_add_u64 v[42:43], v[40:41], 2, s[28:29]
	v_lshl_add_u64 v[50:51], v[48:49], 2, s[28:29]
	v_lshl_add_u64 v[52:53], v[36:37], 2, s[28:29]
	v_ashrrev_i32_e32 v41, 31, v54
	v_lshl_add_u64 v[56:57], v[44:45], 2, s[28:29]
	v_ashrrev_i32_e32 v49, 31, v58
	v_add_u32_e32 v68, 0xc00, v1
	v_add_u32_e32 v70, 0xc40, v1
	v_add_u32_e32 v72, 0xc80, v1
	v_add_u32_e32 v1, 0xcc0, v1
	v_lshl_add_u64 v[54:55], v[40:41], 2, s[28:29]
	v_lshl_add_u64 v[58:59], v[48:49], 2, s[28:29]
	global_load_dword v36, v[38:39], off
	global_load_dword v37, v[42:43], off
	s_nop 0
	global_load_dword v38, v[46:47], off
	global_load_dword v39, v[50:51], off
	global_load_dword v40, v[52:53], off offset:64
	global_load_dword v41, v[54:55], off offset:64
	global_load_dword v44, v[52:53], off offset:128
	global_load_dword v48, v[52:53], off offset:192
	global_load_dword v42, v[56:57], off offset:64
	global_load_dword v43, v[58:59], off offset:64
	global_load_dword v45, v[54:55], off offset:128
	global_load_dword v46, v[56:57], off offset:128
	global_load_dword v47, v[58:59], off offset:128
	global_load_dword v51, v[58:59], off offset:192
	global_load_dword v50, v[56:57], off offset:192
	global_load_dword v49, v[54:55], off offset:192
	v_or_b32_e32 v52, v68, v3
	v_or_b32_e32 v56, v70, v3
	v_or_b32_e32 v60, v72, v3
	v_or_b32_e32 v64, v1, v3
	v_ashrrev_i32_e32 v53, 31, v52
	v_ashrrev_i32_e32 v57, 31, v56
	v_ashrrev_i32_e32 v61, 31, v60
	v_ashrrev_i32_e32 v65, 31, v64
	v_lshl_add_u64 v[54:55], v[52:53], 2, s[28:29]
	v_lshl_add_u64 v[58:59], v[56:57], 2, s[28:29]
	v_lshl_add_u64 v[62:63], v[60:61], 2, s[28:29]
	v_lshl_add_u64 v[66:67], v[64:65], 2, s[28:29]
	v_ashrrev_i32_e32 v53, 31, v68
	v_ashrrev_i32_e32 v57, 31, v70
	v_ashrrev_i32_e32 v61, 31, v72
	v_ashrrev_i32_e32 v65, 31, v1
	v_lshl_add_u64 v[68:69], v[52:53], 2, s[28:29]
	v_lshl_add_u64 v[70:71], v[56:57], 2, s[28:29]
	v_lshl_add_u64 v[72:73], v[60:61], 2, s[28:29]
	v_lshl_add_u64 v[74:75], v[64:65], 2, s[28:29]
	global_load_dword v52, v[54:55], off
	global_load_dword v53, v[58:59], off
	s_nop 0
	global_load_dword v54, v[62:63], off
	global_load_dword v55, v[66:67], off
	global_load_dword v56, v[68:69], off offset:64
	global_load_dword v57, v[70:71], off offset:64
	global_load_dword v60, v[68:69], off offset:128
	global_load_dword v64, v[68:69], off offset:192
	global_load_dword v58, v[72:73], off offset:64
	global_load_dword v59, v[74:75], off offset:64
	global_load_dword v61, v[70:71], off offset:128
	global_load_dword v62, v[72:73], off offset:128
	global_load_dword v63, v[74:75], off offset:128
	global_load_dword v67, v[74:75], off offset:192
	global_load_dword v66, v[72:73], off offset:192
	global_load_dword v65, v[70:71], off offset:192
	v_and_b32_e32 v68, -16, v0
	s_add_u32 s28, s63, s54
	v_add_u32_e32 v146, s58, v68
	v_lshlrev_b32_e32 v68, 4, v0
	s_addc_u32 s29, s62, 0
	v_and_b32_e32 v68, 0x70, v68
	v_mov_b32_e32 v69, v2
	v_add_u32_e32 v73, s58, v68
	v_lshl_add_u64 v[136:137], s[28:29], 0, v[68:69]
	v_ashrrev_i32_e32 v68, 3, v0
	v_mul_lo_u32 v69, v68, s78
	v_mul_lo_u32 v147, v68, s65
	v_add_u32_e32 v68, 64, v0
	v_ashrrev_i32_e32 v1, 31, v0
	s_movk_i32 s3, 0xffc4
	v_sub_u32_e32 v71, v3, v77
	v_lshlrev_b32_e32 v143, 6, v3
	v_ashrrev_i32_e32 v68, 3, v68
	v_lshl_add_u64 v[134:135], v[0:1], 1, s[24:25]
	v_lshl_add_u32 v140, v0, 1, s58
	v_lshl_add_u32 v141, v0, 6, s58
	v_mul_lo_u32 v1, v0, s3
	v_add_u32_e32 v145, s58, v143
	s_movk_i32 s3, 0xffc2
	v_cmp_gt_i32_e64 s[42:43], 2, v71
	v_cmp_gt_i32_e32 vcc, 3, v71
	v_mul_lo_u32 v75, v68, s78
	v_mul_lo_u32 v148, v68, s65
	v_add_u32_e32 v68, 0x80, v0
	v_add_u32_e32 v0, 0xc0, v0
	v_lshlrev_b32_e32 v142, 3, v76
	v_mad_i32_i24 v72, v3, s3, v145
	v_cmp_gt_i32_e64 s[40:41], 1, v71
	s_movk_i32 s3, 0x220
	v_ashrrev_i32_e32 v68, 3, v68
	v_ashrrev_i32_e32 v0, 3, v0
	s_and_b64 s[42:43], vcc, s[42:43]
	v_sub_f32_e32 v133, 1.0, v130
	v_add_u32_e32 v70, s58, v142
	v_mul_u32_u24_e32 v3, 0x88, v3
	v_cmp_gt_i32_e64 s[38:39], 0, v71
	v_mul_lo_u32 v71, v76, s3
	v_mul_lo_u32 v74, v78, s78
	v_mul_lo_u32 v76, v68, s78
	v_mul_lo_u32 v149, v68, s65
	v_mul_lo_u32 v68, v0, s78
	s_and_b64 s[40:41], s[42:43], s[40:41]
	s_mov_b32 s24, 0
	v_mul_lo_u32 v150, v0, s65
	v_mov_b32_e32 v138, v133
	v_mov_b32_e32 v139, v133
	v_mov_b32_e32 v131, v130
	v_add_u32_e32 v151, v141, v1
	v_add_u32_e32 v152, v70, v3
	v_add_u32_e32 v153, v72, v71
	v_add_u32_e32 v154, v72, v74
	v_add_u32_e32 v155, v73, v69
	v_add_u32_e32 v156, v73, v75
	v_add_u32_e32 v157, v73, v76
	v_add_u32_e32 v158, v73, v68
	s_and_b64 s[38:39], s[40:41], s[38:39]
	s_lshl_b32 s101, s65, 4
	s_add_i32 s100, s70, s24
	s_and_b64 s[28:29], s[52:53], exec
	s_cselect_b32 s100, s100, s71
	s_mul_i32 s28, s100, 0xe00
	s_ashr_i32 s29, s28, 31
	v_lshl_add_u64 v[172:173], v[134:135], 0, s[28:29]
	v_lshl_add_u64 v[174:175], v[172:173], 0, s[26:27]
	global_load_ushort v180, v[174:175], off offset:1024
	global_load_ushort v196, v[172:173], off
	global_load_ushort v217, v[172:173], off offset:512
	s_add_i32 s100, s100, s65
	s_mul_i32 s28, s100, 0xe00
	s_ashr_i32 s29, s28, 31
	v_lshl_add_u64 v[172:173], v[134:135], 0, s[28:29]
	v_lshl_add_u64 v[174:175], v[172:173], 0, s[26:27]
	global_load_ushort v181, v[174:175], off offset:1024
	global_load_ushort v197, v[172:173], off
	global_load_ushort v218, v[172:173], off offset:512
	s_add_i32 s100, s100, s65
	s_mul_i32 s28, s100, 0xe00
	s_ashr_i32 s29, s28, 31
	v_lshl_add_u64 v[172:173], v[134:135], 0, s[28:29]
	v_lshl_add_u64 v[174:175], v[172:173], 0, s[26:27]
	global_load_ushort v182, v[174:175], off offset:1024
	global_load_ushort v198, v[172:173], off
	global_load_ushort v219, v[172:173], off offset:512
	s_add_i32 s100, s100, s65
	s_mul_i32 s28, s100, 0xe00
	s_ashr_i32 s29, s28, 31
	v_lshl_add_u64 v[172:173], v[134:135], 0, s[28:29]
	v_lshl_add_u64 v[174:175], v[172:173], 0, s[26:27]
	global_load_ushort v183, v[174:175], off offset:1024
	global_load_ushort v199, v[172:173], off
	global_load_ushort v220, v[172:173], off offset:512
	s_add_i32 s100, s100, s65
	s_mul_i32 s28, s100, 0xe00
	s_ashr_i32 s29, s28, 31
	v_lshl_add_u64 v[172:173], v[134:135], 0, s[28:29]
	v_lshl_add_u64 v[174:175], v[172:173], 0, s[26:27]
	global_load_ushort v184, v[174:175], off offset:1024
	global_load_ushort v200, v[172:173], off
	global_load_ushort v221, v[172:173], off offset:512
	s_add_i32 s100, s100, s65
	s_mul_i32 s28, s100, 0xe00
	s_ashr_i32 s29, s28, 31
	v_lshl_add_u64 v[172:173], v[134:135], 0, s[28:29]
	v_lshl_add_u64 v[174:175], v[172:173], 0, s[26:27]
	global_load_ushort v185, v[174:175], off offset:1024
	global_load_ushort v206, v[172:173], off
	global_load_ushort v222, v[172:173], off offset:512
	s_add_i32 s100, s100, s65
	s_mul_i32 s28, s100, 0xe00
	s_ashr_i32 s29, s28, 31
	v_lshl_add_u64 v[172:173], v[134:135], 0, s[28:29]
	v_lshl_add_u64 v[174:175], v[172:173], 0, s[26:27]
	global_load_ushort v186, v[174:175], off offset:1024
	global_load_ushort v207, v[172:173], off
	global_load_ushort v223, v[172:173], off offset:512
	s_add_i32 s100, s100, s65
	s_mul_i32 s28, s100, 0xe00
	s_ashr_i32 s29, s28, 31
	v_lshl_add_u64 v[172:173], v[134:135], 0, s[28:29]
	v_lshl_add_u64 v[174:175], v[172:173], 0, s[26:27]
	global_load_ushort v187, v[174:175], off offset:1024
	global_load_ushort v208, v[172:173], off
	global_load_ushort v224, v[172:173], off offset:512
	s_add_i32 s100, s100, s65
	s_mul_i32 s28, s100, 0xe00
	s_ashr_i32 s29, s28, 31
	v_lshl_add_u64 v[172:173], v[134:135], 0, s[28:29]
	v_lshl_add_u64 v[174:175], v[172:173], 0, s[26:27]
	global_load_ushort v188, v[174:175], off offset:1024
	global_load_ushort v209, v[172:173], off
	global_load_ushort v225, v[172:173], off offset:512
	s_add_i32 s100, s100, s65
	s_mul_i32 s28, s100, 0xe00
	s_ashr_i32 s29, s28, 31
	v_lshl_add_u64 v[172:173], v[134:135], 0, s[28:29]
	v_lshl_add_u64 v[174:175], v[172:173], 0, s[26:27]
	global_load_ushort v189, v[174:175], off offset:1024
	global_load_ushort v210, v[172:173], off
	global_load_ushort v245, v[172:173], off offset:512
	s_add_i32 s100, s100, s65
	s_mul_i32 s28, s100, 0xe00
	s_ashr_i32 s29, s28, 31
	v_lshl_add_u64 v[172:173], v[134:135], 0, s[28:29]
	v_lshl_add_u64 v[174:175], v[172:173], 0, s[26:27]
	global_load_ushort v190, v[174:175], off offset:1024
	global_load_ushort v211, v[172:173], off
	global_load_ushort v246, v[172:173], off offset:512
	s_add_i32 s100, s100, s65
	s_mul_i32 s28, s100, 0xe00
	s_ashr_i32 s29, s28, 31
	v_lshl_add_u64 v[172:173], v[134:135], 0, s[28:29]
	v_lshl_add_u64 v[174:175], v[172:173], 0, s[26:27]
	global_load_ushort v191, v[174:175], off offset:1024
	global_load_ushort v212, v[172:173], off
	global_load_ushort v248, v[172:173], off offset:512
	s_add_i32 s100, s100, s65
	s_mul_i32 s28, s100, 0xe00
	s_ashr_i32 s29, s28, 31
	v_lshl_add_u64 v[172:173], v[134:135], 0, s[28:29]
	v_lshl_add_u64 v[174:175], v[172:173], 0, s[26:27]
	global_load_ushort v192, v[174:175], off offset:1024
	global_load_ushort v213, v[172:173], off
	global_load_ushort v249, v[172:173], off offset:512
	s_add_i32 s100, s100, s65
	s_mul_i32 s28, s100, 0xe00
	s_ashr_i32 s29, s28, 31
	v_lshl_add_u64 v[172:173], v[134:135], 0, s[28:29]
	v_lshl_add_u64 v[174:175], v[172:173], 0, s[26:27]
	global_load_ushort v193, v[174:175], off offset:1024
	global_load_ushort v214, v[172:173], off
	global_load_ushort v250, v[172:173], off offset:512
	s_add_i32 s100, s100, s65
	s_mul_i32 s28, s100, 0xe00
	s_ashr_i32 s29, s28, 31
	v_lshl_add_u64 v[172:173], v[134:135], 0, s[28:29]
	v_lshl_add_u64 v[174:175], v[172:173], 0, s[26:27]
	global_load_ushort v194, v[174:175], off offset:1024
	global_load_ushort v215, v[172:173], off
	global_load_ushort v251, v[172:173], off offset:512
	s_add_i32 s100, s100, s65
	s_mul_i32 s28, s100, 0xe00
	s_ashr_i32 s29, s28, 31
	v_lshl_add_u64 v[172:173], v[134:135], 0, s[28:29]
	v_lshl_add_u64 v[174:175], v[172:173], 0, s[26:27]
	global_load_ushort v195, v[174:175], off offset:1024
	global_load_ushort v216, v[172:173], off
	global_load_ushort v252, v[172:173], off offset:512
	s_add_i32 s100, s100, s65
	s_waitcnt vmcnt(0)
.LBB0_687:
	s_add_i32 s3, s70, s24
	s_and_b64 s[28:29], s[52:53], exec
	s_cselect_b32 s3, s3, s71
	s_add_i32 s100, s3, s101
	s_mul_i32 s28, s100, 0xe00
	s_ashr_i32 s29, s28, 31
	v_lshl_add_u64 v[68:69], v[134:135], 0, s[28:29]
	v_lshl_add_u64 v[0:1], v[68:69], 0, s[26:27]
	v_mov_b32_e32 v172, v0
	v_mov_b32_e32 v173, v1
	s_waitcnt vmcnt(51)
	v_mov_b32_e32 v0, v180
	global_load_ushort v180, v[172:173], off offset:1024
	s_add_i32 s25, s100, s65
	s_mul_i32 s28, s25, 0xe00
	s_ashr_i32 s29, s28, 31
	v_lshl_add_u64 v[74:75], v[134:135], 0, s[28:29]
	v_lshl_add_u64 v[76:77], v[74:75], 0, s[26:27]
	s_add_i32 s25, s25, s65
	s_mul_i32 s28, s25, 0xe00
	s_ashr_i32 s29, s28, 31
	s_add_i32 s25, s25, s65
	s_add_i32 s24, s24, 32
	s_sub_i32 s71, s71, 32
	s_nop 0
	v_lshlrev_b32_e32 v0, 16, v0
	v_max_f32_e32 v0, v0, v0
	v_max_f32_e32 v1, 0xc2700000, v0
	v_mul_f32_e32 v1, 0xbfb8aa3b, v1
	v_exp_f32_e32 v70, v1
	s_waitcnt vmcnt(51)
	v_mov_b32_e32 v0, v217
	global_load_ushort v217, v[68:69], off offset:512
	v_add_f32_e32 v1, 1.0, v70
	v_rcp_f32_e32 v72, v1
	s_waitcnt vmcnt(51)
	v_mov_b32_e32 v1, v181
	global_load_ushort v181, v[76:77], off offset:1024
	s_nop 0
	v_lshlrev_b32_e32 v1, 16, v1
	v_max_f32_e32 v1, v1, v1
	v_max_f32_e32 v1, 0xc2700000, v1
	v_mul_f32_e32 v1, 0xbfb8aa3b, v1
	v_exp_f32_e32 v71, v1
	s_nop 0
	v_add_f32_e32 v1, 1.0, v71
	v_rcp_f32_e32 v73, v1
	v_pk_mul_f32 v[70:71], v[138:139], v[70:71]
	v_pk_fma_f32 v[76:77], v[138:139], v[72:73], v[130:131]
	s_nop 0
	v_max_f32_e32 v1, 0xda24260, v76
	v_rcp_f32_e32 v78, v1
	s_waitcnt vmcnt(50)
	v_mov_b32_e32 v1, v197
	global_load_ushort v197, v[74:75], off
	s_nop 0
	v_mov_b32_e32 v3, v196
	global_load_ushort v196, v[68:69], off
	v_pk_mul_f32 v[70:71], v[70:71], v[72:73]
	v_lshl_add_u64 v[72:73], v[134:135], 0, s[28:29]
	v_lshl_add_u64 v[80:81], v[72:73], 0, s[26:27]
	v_mov_b32_e32 v132, v76
	v_mov_b32_e32 v82, v77
	s_mul_i32 s28, s25, 0xe00
	s_ashr_i32 s29, s28, 31
	s_add_i32 s25, s25, s65
	s_nop 0
	v_lshlrev_b32_e32 v69, 16, v1
	s_waitcnt vmcnt(51)
	v_mov_b32_e32 v1, v182
	global_load_ushort v182, v[80:81], off offset:1024
	s_nop 0
	v_lshlrev_b32_e32 v68, 16, v3
	s_nop 0
	v_lshlrev_b32_e32 v1, 16, v1
	v_max_f32_e32 v1, v1, v1
	v_max_f32_e32 v3, 0xc2700000, v1
	v_mul_f32_e32 v3, 0xbfb8aa3b, v3
	v_exp_f32_e32 v80, v3
	s_waitcnt vmcnt(50)
	v_mov_b32_e32 v1, v219
	global_load_ushort v219, v[72:73], off offset:512
	v_add_f32_e32 v3, 1.0, v80
	v_rcp_f32_e32 v83, v3
	s_nop 0
	v_pk_mul_f32 v[84:85], v[132:133], v[82:83]
	s_nop 0
	v_max_f32_e32 v3, 0xda24260, v84
	v_rcp_f32_e32 v79, v3
	v_mov_b32_e32 v77, v84
	v_pk_mul_f32 v[76:77], v[76:77], v[68:69]
	v_pk_mul_f32 v[70:71], v[70:71], v[78:79]
	s_nop 0
	v_cvt_pk_bf16_f32 v68, v70, v71
	v_cvt_pk_bf16_f32 v3, v76, v77
	v_lshl_add_u64 v[70:71], v[134:135], 0, s[28:29]
	ds_write_b16 v140, v3
	ds_write_b16_d16_hi v140, v3 offset:136
	ds_write_b16 v140, v68 offset:4352
	ds_write_b16_d16_hi v140, v68 offset:4488
	v_lshl_add_u64 v[76:77], v[70:71], 0, s[26:27]
	s_nop 0
	v_mov_b32_e32 v69, v183
	global_load_ushort v183, v[76:77], off offset:1024
	v_add_f32_e32 v3, v130, v85
	v_mul_f32_e32 v78, v84, v3
	v_max_f32_e32 v3, 0xda24260, v78
	v_rcp_f32_e32 v84, v3
	v_mov_b32_e32 v76, v83
	s_mul_i32 s28, s25, 0xe00
	s_ashr_i32 s29, s28, 31
	s_add_i32 s25, s25, s65
	s_nop 0
	v_lshlrev_b32_e32 v69, 16, v69
	v_max_f32_e32 v69, v69, v69
	v_max_f32_e32 v69, 0xc2700000, v69
	v_mul_f32_e32 v69, 0xbfb8aa3b, v69
	v_exp_f32_e32 v81, v69
	s_nop 0
	v_add_f32_e32 v69, 1.0, v81
	v_rcp_f32_e32 v77, v69
	v_pk_mul_f32 v[80:81], v[138:139], v[80:81]
	v_fma_f32 v69, v133, v77, v130
	v_mul_f32_e32 v79, v78, v69
	s_waitcnt vmcnt(50)
	v_mov_b32_e32 v3, v199
	global_load_ushort v199, v[70:71], off
	s_nop 0
	v_mov_b32_e32 v69, v198
	global_load_ushort v198, v[72:73], off
	v_pk_mul_f32 v[76:77], v[80:81], v[76:77]
	s_nop 0
	v_lshlrev_b32_e32 v73, 16, v3
	v_max_f32_e32 v3, 0xda24260, v79
	v_rcp_f32_e32 v85, v3
	s_nop 0
	v_lshlrev_b32_e32 v72, 16, v69
	v_pk_mul_f32 v[72:73], v[78:79], v[72:73]
	s_waitcnt vmcnt(51)
	v_mov_b32_e32 v3, v220
	global_load_ushort v220, v[70:71], off offset:512
	s_waitcnt vmcnt(51)
	v_mov_b32_e32 v80, v218
	global_load_ushort v218, v[74:75], off offset:512
	v_pk_mul_f32 v[76:77], v[76:77], v[84:85]
	v_cvt_pk_bf16_f32 v72, v72, v73
	v_lshl_add_u64 v[70:71], v[134:135], 0, s[28:29]
	v_cvt_pk_bf16_f32 v69, v76, v77
	ds_write_b16 v140, v72 offset:272
	ds_write_b16_d16_hi v140, v72 offset:408
	ds_write_b16 v140, v69 offset:4624
	ds_write_b16_d16_hi v140, v69 offset:4760
	v_lshl_add_u64 v[72:73], v[70:71], 0, s[26:27]
	v_mov_b32_e32 v172, v72
	v_mov_b32_e32 v173, v73
	s_waitcnt vmcnt(51)
	v_mov_b32_e32 v72, v184
	global_load_ushort v184, v[172:173], off offset:1024
	s_mul_i32 s28, s25, 0xe00
	s_waitcnt vmcnt(51)
	v_mov_b32_e32 v81, v221
	global_load_ushort v221, v[70:71], off offset:512
	s_ashr_i32 s29, s28, 31
	v_lshl_add_u64 v[76:77], v[134:135], 0, s[28:29]
	v_lshl_add_u64 v[82:83], v[76:77], 0, s[26:27]
	s_add_i32 s25, s25, s65
	s_mul_i32 s28, s25, 0xe00
	s_ashr_i32 s29, s28, 31
	s_add_i32 s25, s25, s65
	s_nop 0
	v_lshl_or_b32 v80, v80, 16, v0
	v_add_u32_e32 v0, 0x1000, v152
	s_nop 0
	v_lshlrev_b32_e32 v72, 16, v72
	v_max_f32_e32 v72, v72, v72
	v_max_f32_e32 v72, 0xc2700000, v72
	v_mul_f32_e32 v72, 0xbfb8aa3b, v72
	v_exp_f32_e32 v72, v72
	s_nop 0
	v_add_f32_e32 v73, 1.0, v72
	v_rcp_f32_e32 v74, v73
	s_waitcnt vmcnt(51)
	v_mov_b32_e32 v73, v185
	global_load_ushort v185, v[82:83], off offset:1024
	s_nop 0
	v_mov_b32_e32 v172, v70
	v_mov_b32_e32 v173, v71
	s_waitcnt vmcnt(51)
	v_mov_b32_e32 v70, v200
	global_load_ushort v200, v[172:173], off
	s_nop 0
	s_waitcnt vmcnt(51)
	v_mov_b32_e32 v71, v206
	global_load_ushort v206, v[76:77], off
	v_fma_f32 v78, v133, v74, v130
	v_mul_f32_e32 v78, v79, v78
	v_max_f32_e32 v79, 0xda24260, v78
	v_rcp_f32_e32 v82, v79
	s_nop 0
	v_lshlrev_b32_e32 v70, 16, v70
	v_lshlrev_b32_e32 v73, 16, v73
	v_max_f32_e32 v73, v73, v73
	v_max_f32_e32 v73, 0xc2700000, v73
	v_mul_f32_e32 v73, 0xbfb8aa3b, v73
	v_exp_f32_e32 v73, v73
	s_nop 0
	v_lshlrev_b32_e32 v71, 16, v71
	v_add_f32_e32 v75, 1.0, v73
	v_rcp_f32_e32 v75, v75
	s_nop 0
	v_fma_f32 v83, v133, v75, v130
	v_mul_f32_e32 v79, v78, v83
	v_pk_mul_f32 v[84:85], v[78:79], v[70:71]
	v_max_f32_e32 v70, 0xda24260, v79
	v_rcp_f32_e32 v83, v70
	v_pk_mul_f32 v[70:71], v[138:139], v[72:73]
	v_lshl_add_u64 v[72:73], v[134:135], 0, s[28:29]
	v_pk_mul_f32 v[70:71], v[70:71], v[74:75]
	v_lshl_add_u64 v[74:75], v[72:73], 0, s[26:27]
	v_pk_mul_f32 v[70:71], v[70:71], v[82:83]
	s_waitcnt vmcnt(45)
	v_mov_b32_e32 v82, v222
	global_load_ushort v222, v[76:77], off offset:512
	v_cvt_pk_bf16_f32 v70, v70, v71
	v_cvt_pk_bf16_f32 v71, v84, v85
	ds_write_b16 v140, v71 offset:544
	ds_write_b16_d16_hi v140, v71 offset:680
	ds_write_b16 v140, v70 offset:4896
	ds_write_b16_d16_hi v140, v70 offset:5032
	s_nop 0
	v_mov_b32_e32 v71, v186
	global_load_ushort v186, v[74:75], off offset:1024
	s_nop 0
	v_mov_b32_e32 v83, v223
	global_load_ushort v223, v[72:73], off offset:512
	s_mul_i32 s28, s25, 0xe00
	s_ashr_i32 s29, s28, 31
	v_lshl_add_u64 v[84:85], v[134:135], 0, s[28:29]
	v_lshl_add_u64 v[86:87], v[84:85], 0, s[26:27]
	s_nop 0
	v_mov_b32_e32 v75, v187
	global_load_ushort v187, v[86:87], off offset:1024
	s_add_i32 s25, s25, s65
	s_mul_i32 s28, s25, 0xe00
	s_ashr_i32 s29, s28, 31
	s_add_i32 s25, s25, s65
	s_nop 0
	v_lshl_or_b32 v82, v82, 16, v81
	v_lshl_or_b32 v81, v3, 16, v1
	v_add_u32_e32 v1, 0x1800, v152
	s_nop 0
	v_lshlrev_b32_e32 v71, 16, v71
	v_max_f32_e32 v71, v71, v71
	v_max_f32_e32 v71, 0xc2700000, v71
	v_mul_f32_e32 v71, 0xbfb8aa3b, v71
	v_exp_f32_e32 v74, v71
	s_nop 0
	v_lshlrev_b32_e32 v75, 16, v75
	v_max_f32_e32 v75, v75, v75
	v_add_f32_e32 v71, 1.0, v74
	v_rcp_f32_e32 v76, v71
	v_max_f32_e32 v75, 0xc2700000, v75
	v_mul_f32_e32 v75, 0xbfb8aa3b, v75
	v_exp_f32_e32 v75, v75
	v_fma_f32 v71, v133, v76, v130
	v_mul_f32_e32 v78, v79, v71
	v_max_f32_e32 v71, 0xda24260, v78
	v_rcp_f32_e32 v86, v71
	s_nop 0
	v_mov_b32_e32 v71, v207
	global_load_ushort v207, v[72:73], off
	s_nop 0
	s_nop 0
	v_mov_b32_e32 v72, v208
	global_load_ushort v208, v[84:85], off
	v_add_f32_e32 v77, 1.0, v75
	v_rcp_f32_e32 v77, v77
	v_pk_mul_f32 v[74:75], v[138:139], v[74:75]
	v_mov_b32_e32 v172, v84
	v_mov_b32_e32 v173, v85
	s_nop 0
	v_mov_b32_e32 v84, v224
	global_load_ushort v224, v[172:173], off offset:512
	v_fma_f32 v87, v133, v77, v130
	v_mul_f32_e32 v79, v78, v87
	v_pk_mul_f32 v[74:75], v[74:75], v[76:77]
	s_nop 0
	v_lshlrev_b32_e32 v73, 16, v72
	v_lshlrev_b32_e32 v72, 16, v71
	v_max_f32_e32 v71, 0xda24260, v79
	v_rcp_f32_e32 v87, v71
	v_pk_mul_f32 v[72:73], v[78:79], v[72:73]
	s_nop 0
	v_lshl_or_b32 v83, v84, 16, v83
	v_cvt_pk_bf16_f32 v72, v72, v73
	v_pk_mul_f32 v[74:75], v[74:75], v[86:87]
	s_nop 0
	v_cvt_pk_bf16_f32 v71, v74, v75
	ds_write_b16 v140, v72 offset:816
	ds_write_b16_d16_hi v140, v72 offset:952
	ds_write_b16 v140, v71 offset:5168
	ds_write_b16_d16_hi v140, v71 offset:5304
	v_lshl_add_u64 v[72:73], v[134:135], 0, s[28:29]
	v_lshl_add_u64 v[74:75], v[72:73], 0, s[26:27]
	v_mov_b32_e32 v172, v74
	v_mov_b32_e32 v173, v75
	s_waitcnt vmcnt(51)
	v_mov_b32_e32 v74, v188
	global_load_ushort v188, v[172:173], off offset:1024
	s_mul_i32 s28, s25, 0xe00
	s_waitcnt vmcnt(51)
	v_mov_b32_e32 v85, v225
	global_load_ushort v225, v[72:73], off offset:512
	s_ashr_i32 s29, s28, 31
	v_lshl_add_u64 v[86:87], v[134:135], 0, s[28:29]
	v_lshl_add_u64 v[88:89], v[86:87], 0, s[26:27]
	s_add_i32 s25, s25, s65
	s_mul_i32 s28, s25, 0xe00
	s_ashr_i32 s29, s28, 31
	s_add_i32 s25, s25, s65
	s_nop 0
	v_lshlrev_b32_e32 v74, 16, v74
	v_max_f32_e32 v74, v74, v74
	v_max_f32_e32 v74, 0xc2700000, v74
	v_mul_f32_e32 v74, 0xbfb8aa3b, v74
	v_exp_f32_e32 v74, v74
	s_nop 0
	v_add_f32_e32 v75, 1.0, v74
	v_rcp_f32_e32 v76, v75
	s_waitcnt vmcnt(51)
	v_mov_b32_e32 v75, v189
	global_load_ushort v189, v[88:89], off offset:1024
	s_nop 0
	v_mov_b32_e32 v172, v72
	v_mov_b32_e32 v173, v73
	s_waitcnt vmcnt(51)
	v_mov_b32_e32 v72, v209
	global_load_ushort v209, v[172:173], off
	s_nop 0
	s_waitcnt vmcnt(51)
	v_mov_b32_e32 v73, v210
	global_load_ushort v210, v[86:87], off
	v_fma_f32 v78, v133, v76, v130
	v_mul_f32_e32 v78, v79, v78
	v_max_f32_e32 v79, 0xda24260, v78
	v_rcp_f32_e32 v88, v79
	v_mov_b32_e32 v172, v86
	v_mov_b32_e32 v173, v87
	s_waitcnt vmcnt(45)
	v_mov_b32_e32 v86, v245
	global_load_ushort v245, v[172:173], off offset:512
	s_nop 0
	v_lshlrev_b32_e32 v72, 16, v72
	v_lshlrev_b32_e32 v75, 16, v75
	v_max_f32_e32 v75, v75, v75
	v_max_f32_e32 v75, 0xc2700000, v75
	v_mul_f32_e32 v75, 0xbfb8aa3b, v75
	v_exp_f32_e32 v75, v75
	s_nop 0
	v_lshlrev_b32_e32 v73, 16, v73
	v_add_f32_e32 v77, 1.0, v75
	v_rcp_f32_e32 v77, v77
	s_nop 0
	v_fma_f32 v89, v133, v77, v130
	v_mul_f32_e32 v79, v78, v89
	v_pk_mul_f32 v[90:91], v[78:79], v[72:73]
	v_max_f32_e32 v72, 0xda24260, v79
	v_rcp_f32_e32 v89, v72
	v_pk_mul_f32 v[72:73], v[138:139], v[74:75]
	v_lshl_add_u64 v[74:75], v[134:135], 0, s[28:29]
	v_pk_mul_f32 v[72:73], v[72:73], v[76:77]
	v_lshl_add_u64 v[76:77], v[74:75], 0, s[26:27]
	v_pk_mul_f32 v[72:73], v[72:73], v[88:89]
	s_mul_i32 s28, s25, 0xe00
	v_cvt_pk_bf16_f32 v72, v72, v73
	v_cvt_pk_bf16_f32 v73, v90, v91
	ds_write_b16 v140, v73 offset:1088
	ds_write_b16_d16_hi v140, v73 offset:1224
	ds_write_b16 v140, v72 offset:5440
	ds_write_b16_d16_hi v140, v72 offset:5576
	s_nop 0
	v_mov_b32_e32 v73, v190
	global_load_ushort v190, v[76:77], off offset:1024
	s_nop 0
	v_mov_b32_e32 v87, v246
	global_load_ushort v246, v[74:75], off offset:512
	s_ashr_i32 s29, s28, 31
	v_lshl_add_u64 v[90:91], v[134:135], 0, s[28:29]
	v_lshl_add_u64 v[92:93], v[90:91], 0, s[26:27]
	s_nop 0
	v_mov_b32_e32 v77, v191
	global_load_ushort v191, v[92:93], off offset:1024
	s_add_i32 s25, s25, s65
	s_mul_i32 s28, s25, 0xe00
	s_ashr_i32 s29, s28, 31
	s_add_i32 s25, s25, s65
	s_nop 0
	v_lshlrev_b32_e32 v73, 16, v73
	v_max_f32_e32 v73, v73, v73
	v_max_f32_e32 v73, 0xc2700000, v73
	v_mul_f32_e32 v73, 0xbfb8aa3b, v73
	v_exp_f32_e32 v76, v73
	s_nop 0
	v_lshlrev_b32_e32 v77, 16, v77
	v_max_f32_e32 v77, v77, v77
	v_max_f32_e32 v77, 0xc2700000, v77
	v_add_f32_e32 v73, 1.0, v76
	v_mul_f32_e32 v77, 0xbfb8aa3b, v77
	v_rcp_f32_e32 v88, v73
	v_exp_f32_e32 v77, v77
	v_fma_f32 v73, v133, v88, v130
	v_add_f32_e32 v78, 1.0, v77
	v_rcp_f32_e32 v89, v78
	v_mul_f32_e32 v78, v79, v73
	v_max_f32_e32 v73, 0xda24260, v78
	v_rcp_f32_e32 v92, v73
	s_nop 0
	v_mov_b32_e32 v73, v211
	global_load_ushort v211, v[74:75], off
	s_nop 0
	s_nop 0
	v_mov_b32_e32 v74, v212
	global_load_ushort v212, v[90:91], off
	v_fma_f32 v93, v133, v89, v130
	v_mul_f32_e32 v79, v78, v93
	v_pk_mul_f32 v[76:77], v[138:139], v[76:77]
	s_nop 0
	v_lshlrev_b32_e32 v75, 16, v74
	v_lshlrev_b32_e32 v74, 16, v73
	v_max_f32_e32 v73, 0xda24260, v79
	v_rcp_f32_e32 v93, v73
	v_pk_mul_f32 v[74:75], v[78:79], v[74:75]
	v_pk_mul_f32 v[76:77], v[76:77], v[88:89]
	v_cvt_pk_bf16_f32 v74, v74, v75
	v_pk_mul_f32 v[76:77], v[76:77], v[92:93]
	s_nop 0
	v_mov_b32_e32 v88, v248
	global_load_ushort v248, v[90:91], off offset:512
	v_cvt_pk_bf16_f32 v73, v76, v77
	ds_write_b16 v140, v74 offset:1360
	ds_write_b16_d16_hi v140, v74 offset:1496
	ds_write_b16 v140, v73 offset:5712
	ds_write_b16_d16_hi v140, v73 offset:5848
	v_lshl_add_u64 v[74:75], v[134:135], 0, s[28:29]
	v_lshl_add_u64 v[76:77], v[74:75], 0, s[26:27]
	v_mov_b32_e32 v172, v76
	v_mov_b32_e32 v173, v77
	s_waitcnt vmcnt(51)
	v_mov_b32_e32 v76, v192
	global_load_ushort v192, v[172:173], off offset:1024
	s_mul_i32 s28, s25, 0xe00
	s_waitcnt vmcnt(51)
	v_mov_b32_e32 v89, v249
	global_load_ushort v249, v[74:75], off offset:512
	s_ashr_i32 s29, s28, 31
	v_lshl_add_u64 v[92:93], v[134:135], 0, s[28:29]
	v_lshl_add_u64 v[94:95], v[92:93], 0, s[26:27]
	s_add_i32 s25, s25, s65
	s_mul_i32 s28, s25, 0xe00
	s_ashr_i32 s29, s28, 31
	s_add_i32 s25, s25, s65
	s_nop 0
	v_lshlrev_b32_e32 v76, 16, v76
	v_max_f32_e32 v76, v76, v76
	v_max_f32_e32 v76, 0xc2700000, v76
	v_mul_f32_e32 v76, 0xbfb8aa3b, v76
	v_exp_f32_e32 v76, v76
	s_nop 0
	v_add_f32_e32 v77, 1.0, v76
	v_rcp_f32_e32 v90, v77
	s_waitcnt vmcnt(51)
	v_mov_b32_e32 v77, v193
	global_load_ushort v193, v[94:95], off offset:1024
	s_nop 0
	v_mov_b32_e32 v172, v74
	v_mov_b32_e32 v173, v75
	s_waitcnt vmcnt(51)
	v_mov_b32_e32 v74, v213
	global_load_ushort v213, v[172:173], off
	s_nop 0
	s_waitcnt vmcnt(51)
	v_mov_b32_e32 v75, v214
	global_load_ushort v214, v[92:93], off
	s_waitcnt vmcnt(51)
	v_mov_b32_e32 v108, v250
	global_load_ushort v250, v[92:93], off offset:512
	v_fma_f32 v78, v133, v90, v130
	v_mul_f32_e32 v78, v79, v78
	v_max_f32_e32 v79, 0xda24260, v78
	v_rcp_f32_e32 v94, v79
	s_nop 0
	v_lshlrev_b32_e32 v74, 16, v74
	v_lshlrev_b32_e32 v77, 16, v77
	v_max_f32_e32 v77, v77, v77
	v_max_f32_e32 v77, 0xc2700000, v77
	v_mul_f32_e32 v77, 0xbfb8aa3b, v77
	v_exp_f32_e32 v77, v77
	s_nop 0
	v_lshlrev_b32_e32 v75, 16, v75
	v_add_f32_e32 v91, 1.0, v77
	v_rcp_f32_e32 v91, v91
	s_nop 0
	v_fma_f32 v95, v133, v91, v130
	v_mul_f32_e32 v79, v78, v95
	v_pk_mul_f32 v[96:97], v[78:79], v[74:75]
	v_max_f32_e32 v74, 0xda24260, v79
	v_rcp_f32_e32 v95, v74
	v_pk_mul_f32 v[74:75], v[138:139], v[76:77]
	v_lshl_add_u64 v[76:77], v[134:135], 0, s[28:29]
	v_pk_mul_f32 v[74:75], v[74:75], v[90:91]
	v_lshl_add_u64 v[90:91], v[76:77], 0, s[26:27]
	v_pk_mul_f32 v[74:75], v[74:75], v[94:95]
	s_mul_i32 s28, s25, 0xe00
	v_cvt_pk_bf16_f32 v74, v74, v75
	v_cvt_pk_bf16_f32 v75, v96, v97
	ds_write_b16 v140, v75 offset:1632
	ds_write_b16_d16_hi v140, v75 offset:1768
	ds_write_b16 v140, v74 offset:5984
	ds_write_b16_d16_hi v140, v74 offset:6120
	s_waitcnt vmcnt(51)
	v_mov_b32_e32 v75, v194
	global_load_ushort v194, v[90:91], off offset:1024
	s_ashr_i32 s29, s28, 31
	v_lshl_add_u64 v[94:95], v[134:135], 0, s[28:29]
	v_lshl_add_u64 v[96:97], v[94:95], 0, s[26:27]
	s_waitcnt vmcnt(50)
	v_mov_b32_e32 v78, v195
	global_load_ushort v195, v[96:97], off offset:1024
	s_nop 0
	v_mov_b32_e32 v109, v251
	global_load_ushort v251, v[76:77], off offset:512
	s_add_i32 s25, s25, s65
	s_mul_i32 s28, s25, 0xe00
	s_ashr_i32 s29, s28, 31
	s_add_i32 s25, s25, s65
	s_nop 0
	v_lshlrev_b32_e32 v75, 16, v75
	v_max_f32_e32 v75, v75, v75
	v_max_f32_e32 v75, 0xc2700000, v75
	v_mul_f32_e32 v75, 0xbfb8aa3b, v75
	v_exp_f32_e32 v90, v75
	s_nop 0
	v_lshlrev_b32_e32 v78, 16, v78
	v_max_f32_e32 v78, v78, v78
	v_max_f32_e32 v78, 0xc2700000, v78
	v_add_f32_e32 v75, 1.0, v90
	v_mul_f32_e32 v78, 0xbfb8aa3b, v78
	v_rcp_f32_e32 v92, v75
	v_exp_f32_e32 v91, v78
	v_fma_f32 v75, v133, v92, v130
	v_add_f32_e32 v78, 1.0, v91
	v_rcp_f32_e32 v93, v78
	v_mul_f32_e32 v78, v79, v75
	v_max_f32_e32 v75, 0xda24260, v78
	v_rcp_f32_e32 v96, v75
	s_waitcnt vmcnt(51)
	v_mov_b32_e32 v75, v215
	global_load_ushort v215, v[76:77], off
	s_nop 0
	s_waitcnt vmcnt(51)
	v_mov_b32_e32 v76, v216
	global_load_ushort v216, v[94:95], off
	v_fma_f32 v97, v133, v93, v130
	v_mul_f32_e32 v79, v78, v97
	v_pk_mul_f32 v[90:91], v[138:139], v[90:91]
	s_waitcnt vmcnt(51)
	v_mov_b32_e32 v110, v252
	global_load_ushort v252, v[94:95], off offset:512
	v_pk_mul_f32 v[90:91], v[90:91], v[92:93]
	s_nop 0
	v_lshlrev_b32_e32 v77, 16, v76
	v_lshlrev_b32_e32 v76, 16, v75
	v_max_f32_e32 v75, 0xda24260, v79
	v_rcp_f32_e32 v97, v75
	v_pk_mul_f32 v[76:77], v[78:79], v[76:77]
	v_pk_mul_f32 v[90:91], v[90:91], v[96:97]
	v_cvt_pk_bf16_f32 v76, v76, v77
	v_cvt_pk_bf16_f32 v75, v90, v91
	ds_write_b16 v140, v76 offset:1904
	ds_write_b16_d16_hi v140, v76 offset:2040
	ds_write_b16 v140, v75 offset:6256
	ds_write_b16_d16_hi v140, v75 offset:6392
	v_lshl_add_u64 v[76:77], v[134:135], 0, s[28:29]
	s_mul_i32 s28, s25, 0xe00
	v_lshl_add_u64 v[90:91], v[76:77], 0, s[26:27]
	s_ashr_i32 s29, s28, 31
	s_waitcnt vmcnt(47)
	v_mov_b32_e32 v78, v180
	global_load_ushort v180, v[90:91], off offset:1024
	s_waitcnt vmcnt(47)
	v_mov_b32_e32 v111, v217
	global_load_ushort v217, v[76:77], off offset:512
	v_lshl_add_u64 v[94:95], v[134:135], 0, s[28:29]
	v_lshl_add_u64 v[96:97], v[94:95], 0, s[26:27]
	s_waitcnt vmcnt(47)
	v_mov_b32_e32 v91, v181
	global_load_ushort v181, v[96:97], off offset:1024
	s_nop 0
	v_mov_b32_e32 v172, v76
	v_mov_b32_e32 v173, v77
	s_waitcnt vmcnt(46)
	v_mov_b32_e32 v76, v196
	global_load_ushort v196, v[172:173], off
	s_nop 0
	s_nop 0
	v_mov_b32_e32 v77, v197
	global_load_ushort v197, v[94:95], off
	s_add_i32 s25, s25, s65
	s_mul_i32 s28, s25, 0xe00
	s_ashr_i32 s29, s28, 31
	s_add_i32 s25, s25, s65
	s_nop 0
	v_lshlrev_b32_e32 v78, 16, v78
	v_max_f32_e32 v78, v78, v78
	v_max_f32_e32 v78, 0xc2700000, v78
	v_mul_f32_e32 v78, 0xbfb8aa3b, v78
	s_nop 0
	v_lshlrev_b32_e32 v91, 16, v91
	v_max_f32_e32 v91, v91, v91
	v_exp_f32_e32 v90, v78
	v_max_f32_e32 v91, 0xc2700000, v91
	v_mul_f32_e32 v91, 0xbfb8aa3b, v91
	v_exp_f32_e32 v91, v91
	v_add_f32_e32 v78, 1.0, v90
	v_rcp_f32_e32 v92, v78
	s_nop 0
	v_lshlrev_b32_e32 v77, 16, v77
	v_add_f32_e32 v93, 1.0, v91
	v_rcp_f32_e32 v93, v93
	v_fma_f32 v78, v133, v92, v130
	v_mul_f32_e32 v78, v79, v78
	v_max_f32_e32 v79, 0xda24260, v78
	v_fma_f32 v97, v133, v93, v130
	v_rcp_f32_e32 v96, v79
	v_mul_f32_e32 v79, v78, v97
	v_lshlrev_b32_e32 v76, 16, v76
	v_pk_mul_f32 v[98:99], v[78:79], v[76:77]
	v_max_f32_e32 v76, 0xda24260, v79
	v_rcp_f32_e32 v97, v76
	v_pk_mul_f32 v[76:77], v[138:139], v[90:91]
	v_lshl_add_u64 v[90:91], v[134:135], 0, s[28:29]
	v_pk_mul_f32 v[76:77], v[76:77], v[92:93]
	v_lshl_add_u64 v[92:93], v[90:91], 0, s[26:27]
	v_pk_mul_f32 v[76:77], v[76:77], v[96:97]
	s_mul_i32 s28, s25, 0xe00
	v_cvt_pk_bf16_f32 v76, v76, v77
	v_cvt_pk_bf16_f32 v77, v98, v99
	ds_write_b16 v140, v77 offset:2176
	ds_write_b16_d16_hi v140, v77 offset:2312
	ds_write_b16 v140, v76 offset:6528
	ds_write_b16_d16_hi v140, v76 offset:6664
	s_waitcnt vmcnt(47)
	v_mov_b32_e32 v77, v182
	global_load_ushort v182, v[92:93], off offset:1024
	s_ashr_i32 s29, s28, 31
	v_lshl_add_u64 v[98:99], v[134:135], 0, s[28:29]
	v_lshl_add_u64 v[100:101], v[98:99], 0, s[26:27]
	s_waitcnt vmcnt(46)
	v_mov_b32_e32 v78, v183
	global_load_ushort v183, v[100:101], off offset:1024
	s_nop 0
	v_mov_b32_e32 v112, v219
	global_load_ushort v219, v[90:91], off offset:512
	s_add_i32 s25, s25, s65
	s_mul_i32 s28, s25, 0xe00
	s_ashr_i32 s29, s28, 31
	s_add_i32 s25, s25, s65
	s_nop 0
	v_lshlrev_b32_e32 v77, 16, v77
	v_max_f32_e32 v77, v77, v77
	v_max_f32_e32 v77, 0xc2700000, v77
	v_mul_f32_e32 v77, 0xbfb8aa3b, v77
	v_exp_f32_e32 v92, v77
	s_nop 0
	v_lshlrev_b32_e32 v78, 16, v78
	v_max_f32_e32 v78, v78, v78
	v_max_f32_e32 v78, 0xc2700000, v78
	v_add_f32_e32 v77, 1.0, v92
	v_mul_f32_e32 v78, 0xbfb8aa3b, v78
	v_rcp_f32_e32 v96, v77
	v_exp_f32_e32 v93, v78
	v_fma_f32 v77, v133, v96, v130
	v_add_f32_e32 v78, 1.0, v93
	v_rcp_f32_e32 v97, v78
	v_mul_f32_e32 v78, v79, v77
	v_max_f32_e32 v77, 0xda24260, v78
	v_rcp_f32_e32 v100, v77
	s_waitcnt vmcnt(46)
	v_mov_b32_e32 v77, v198
	global_load_ushort v198, v[90:91], off
	s_nop 0
	s_nop 0
	v_mov_b32_e32 v90, v199
	global_load_ushort v199, v[98:99], off
	v_fma_f32 v101, v133, v97, v130
	v_mul_f32_e32 v79, v78, v101
	v_pk_mul_f32 v[92:93], v[138:139], v[92:93]
	s_nop 0
	v_lshlrev_b32_e32 v91, 16, v90
	v_lshlrev_b32_e32 v90, 16, v77
	v_max_f32_e32 v77, 0xda24260, v79
	v_rcp_f32_e32 v101, v77
	v_pk_mul_f32 v[90:91], v[78:79], v[90:91]
	v_pk_mul_f32 v[92:93], v[92:93], v[96:97]
	v_cvt_pk_bf16_f32 v78, v90, v91
	v_pk_mul_f32 v[92:93], v[92:93], v[100:101]
	v_lshl_add_u64 v[90:91], v[134:135], 0, s[28:29]
	s_mul_i32 s28, s25, 0xe00
	v_cvt_pk_bf16_f32 v77, v92, v93
	ds_write_b16 v140, v78 offset:2448
	ds_write_b16_d16_hi v140, v78 offset:2584
	ds_write_b16 v140, v77 offset:6800
	ds_write_b16_d16_hi v140, v77 offset:6936
	s_ashr_i32 s29, s28, 31
	v_lshl_add_u64 v[92:93], v[90:91], 0, s[26:27]
	s_waitcnt vmcnt(47)
	v_mov_b32_e32 v113, v220
	global_load_ushort v220, v[98:99], off offset:512
	s_waitcnt vmcnt(47)
	v_mov_b32_e32 v114, v218
	global_load_ushort v218, v[94:95], off offset:512
	s_waitcnt vmcnt(47)
	v_mov_b32_e32 v78, v184
	global_load_ushort v184, v[92:93], off offset:1024
	v_lshl_add_u64 v[96:97], v[134:135], 0, s[28:29]
	v_lshl_add_u64 v[98:99], v[96:97], 0, s[26:27]
	s_waitcnt vmcnt(47)
	v_mov_b32_e32 v115, v221
	global_load_ushort v221, v[90:91], off offset:512
	s_waitcnt vmcnt(47)
	v_mov_b32_e32 v93, v185
	global_load_ushort v185, v[98:99], off offset:1024
	s_nop 0
	v_mov_b32_e32 v172, v90
	v_mov_b32_e32 v173, v91
	s_waitcnt vmcnt(47)
	v_mov_b32_e32 v90, v200
	global_load_ushort v200, v[172:173], off
	s_nop 0
	s_waitcnt vmcnt(47)
	v_mov_b32_e32 v91, v206
	global_load_ushort v206, v[96:97], off
	s_add_i32 s25, s25, s65
	s_mul_i32 s28, s25, 0xe00
	s_ashr_i32 s29, s28, 31
	s_add_i32 s25, s25, s65
	s_nop 0
	v_lshlrev_b32_e32 v78, 16, v78
	v_max_f32_e32 v78, v78, v78
	v_max_f32_e32 v78, 0xc2700000, v78
	v_mul_f32_e32 v78, 0xbfb8aa3b, v78
	s_nop 0
	v_lshlrev_b32_e32 v93, 16, v93
	v_max_f32_e32 v93, v93, v93
	v_exp_f32_e32 v92, v78
	v_max_f32_e32 v93, 0xc2700000, v93
	v_mul_f32_e32 v93, 0xbfb8aa3b, v93
	v_exp_f32_e32 v93, v93
	v_add_f32_e32 v78, 1.0, v92
	v_rcp_f32_e32 v94, v78
	s_nop 0
	v_lshlrev_b32_e32 v91, 16, v91
	v_add_f32_e32 v95, 1.0, v93
	v_rcp_f32_e32 v95, v95
	v_fma_f32 v78, v133, v94, v130
	v_mul_f32_e32 v78, v79, v78
	v_max_f32_e32 v79, 0xda24260, v78
	v_fma_f32 v99, v133, v95, v130
	v_rcp_f32_e32 v98, v79
	v_mul_f32_e32 v79, v78, v99
	v_lshlrev_b32_e32 v90, 16, v90
	v_pk_mul_f32 v[90:91], v[78:79], v[90:91]
	v_max_f32_e32 v78, 0xda24260, v79
	v_rcp_f32_e32 v99, v78
	v_pk_mul_f32 v[92:93], v[138:139], v[92:93]
	v_cvt_pk_bf16_f32 v90, v90, v91
	v_pk_mul_f32 v[92:93], v[92:93], v[94:95]
	s_nop 0
	v_pk_mul_f32 v[92:93], v[92:93], v[98:99]
	s_nop 0
	v_cvt_pk_bf16_f32 v78, v92, v93
	ds_write_b16 v140, v90 offset:2720
	ds_write_b16_d16_hi v140, v90 offset:2856
	ds_write_b16 v140, v78 offset:7072
	ds_write_b16_d16_hi v140, v78 offset:7208
	v_lshl_add_u64 v[90:91], v[134:135], 0, s[28:29]
	v_lshl_add_u64 v[92:93], v[90:91], 0, s[26:27]
	v_mov_b32_e32 v172, v92
	v_mov_b32_e32 v173, v93
	s_waitcnt vmcnt(46)
	v_mov_b32_e32 v92, v186
	global_load_ushort v186, v[172:173], off offset:1024
	s_mul_i32 s28, s25, 0xe00
	s_waitcnt vmcnt(46)
	v_mov_b32_e32 v116, v223
	global_load_ushort v223, v[90:91], off offset:512
	s_ashr_i32 s29, s28, 31
	v_lshl_add_u64 v[98:99], v[134:135], 0, s[28:29]
	v_lshl_add_u64 v[100:101], v[98:99], 0, s[26:27]
	s_add_i32 s25, s25, s65
	s_mul_i32 s28, s25, 0xe00
	s_ashr_i32 s29, s28, 31
	s_add_i32 s25, s25, s65
	s_nop 0
	v_lshlrev_b32_e32 v92, 16, v92
	v_max_f32_e32 v92, v92, v92
	v_max_f32_e32 v92, 0xc2700000, v92
	v_mul_f32_e32 v92, 0xbfb8aa3b, v92
	v_exp_f32_e32 v92, v92
	s_nop 0
	v_add_f32_e32 v93, 1.0, v92
	v_rcp_f32_e32 v94, v93
	s_waitcnt vmcnt(46)
	v_mov_b32_e32 v93, v187
	global_load_ushort v187, v[100:101], off offset:1024
	v_fma_f32 v102, v133, v94, v130
	v_mul_f32_e32 v100, v79, v102
	v_max_f32_e32 v79, 0xda24260, v100
	v_rcp_f32_e32 v102, v79
	s_waitcnt vmcnt(46)
	v_mov_b32_e32 v79, v207
	global_load_ushort v207, v[90:91], off
	s_nop 0
	s_waitcnt vmcnt(46)
	v_mov_b32_e32 v90, v208
	global_load_ushort v208, v[98:99], off
	s_nop 0
	v_lshlrev_b32_e32 v93, 16, v93
	v_max_f32_e32 v93, v93, v93
	v_max_f32_e32 v93, 0xc2700000, v93
	v_mul_f32_e32 v93, 0xbfb8aa3b, v93
	v_exp_f32_e32 v93, v93
	s_nop 0
	v_lshlrev_b32_e32 v91, 16, v90
	v_add_f32_e32 v95, 1.0, v93
	v_rcp_f32_e32 v95, v95
	v_lshlrev_b32_e32 v90, 16, v79
	v_pk_mul_f32 v[92:93], v[138:139], v[92:93]
	v_fma_f32 v101, v133, v95, v130
	v_mul_f32_e32 v101, v100, v101
	v_max_f32_e32 v79, 0xda24260, v101
	v_rcp_f32_e32 v103, v79
	v_pk_mul_f32 v[90:91], v[100:101], v[90:91]
	v_pk_mul_f32 v[92:93], v[92:93], v[94:95]
	v_cvt_pk_bf16_f32 v90, v90, v91
	v_pk_mul_f32 v[92:93], v[92:93], v[102:103]
	s_nop 0
	v_cvt_pk_bf16_f32 v79, v92, v93
	ds_write_b16 v140, v90 offset:2992
	ds_write_b16_d16_hi v140, v90 offset:3128
	ds_write_b16 v140, v79 offset:7344
	ds_write_b16_d16_hi v140, v79 offset:7480
	v_lshl_add_u64 v[90:91], v[134:135], 0, s[28:29]
	v_lshl_add_u64 v[92:93], v[90:91], 0, s[26:27]
	s_waitcnt vmcnt(46)
	v_mov_b32_e32 v117, v224
	global_load_ushort v224, v[98:99], off offset:512
	s_nop 0
	v_mov_b32_e32 v118, v222
	global_load_ushort v222, v[96:97], off offset:512
	s_nop 0
	v_mov_b32_e32 v172, v92
	v_mov_b32_e32 v173, v93
	s_waitcnt vmcnt(47)
	v_mov_b32_e32 v92, v188
	global_load_ushort v188, v[172:173], off offset:1024
	s_mul_i32 s28, s25, 0xe00
	s_ashr_i32 s29, s28, 31
	v_lshl_add_u64 v[96:97], v[134:135], 0, s[28:29]
	v_lshl_add_u64 v[98:99], v[96:97], 0, s[26:27]
	s_waitcnt vmcnt(47)
	v_mov_b32_e32 v119, v225
	global_load_ushort v225, v[90:91], off offset:512
	s_add_i32 s25, s25, s65
	s_mul_i32 s28, s25, 0xe00
	s_ashr_i32 s29, s28, 31
	s_add_i32 s25, s25, s65
	s_nop 0
	v_lshlrev_b32_e32 v92, 16, v92
	v_max_f32_e32 v92, v92, v92
	v_max_f32_e32 v92, 0xc2700000, v92
	v_mul_f32_e32 v92, 0xbfb8aa3b, v92
	v_exp_f32_e32 v92, v92
	s_nop 0
	v_add_f32_e32 v93, 1.0, v92
	v_rcp_f32_e32 v94, v93
	s_waitcnt vmcnt(47)
	v_mov_b32_e32 v93, v189
	global_load_ushort v189, v[98:99], off offset:1024
	s_nop 0
	v_mov_b32_e32 v172, v90
	v_mov_b32_e32 v173, v91
	s_waitcnt vmcnt(47)
	v_mov_b32_e32 v90, v209
	global_load_ushort v209, v[172:173], off
	s_nop 0
	s_waitcnt vmcnt(47)
	v_mov_b32_e32 v91, v210
	global_load_ushort v210, v[96:97], off
	v_fma_f32 v100, v133, v94, v130
	v_mul_f32_e32 v98, v101, v100
	v_max_f32_e32 v100, 0xda24260, v98
	v_rcp_f32_e32 v100, v100
	s_nop 0
	v_lshlrev_b32_e32 v93, 16, v93
	v_max_f32_e32 v93, v93, v93
	v_max_f32_e32 v93, 0xc2700000, v93
	v_mul_f32_e32 v93, 0xbfb8aa3b, v93
	v_exp_f32_e32 v93, v93
	s_nop 0
	v_lshlrev_b32_e32 v91, 16, v91
	v_lshlrev_b32_e32 v90, 16, v90
	v_add_f32_e32 v95, 1.0, v93
	v_rcp_f32_e32 v95, v95
	s_nop 0
	v_fma_f32 v99, v133, v95, v130
	v_mul_f32_e32 v99, v98, v99
	v_pk_mul_f32 v[102:103], v[98:99], v[90:91]
	v_max_f32_e32 v90, 0xda24260, v99
	v_rcp_f32_e32 v101, v90
	v_pk_mul_f32 v[90:91], v[138:139], v[92:93]
	v_lshl_add_u64 v[92:93], v[134:135], 0, s[28:29]
	v_pk_mul_f32 v[90:91], v[90:91], v[94:95]
	v_lshl_add_u64 v[94:95], v[92:93], 0, s[26:27]
	v_pk_mul_f32 v[90:91], v[90:91], v[100:101]
	s_mul_i32 s28, s25, 0xe00
	v_cvt_pk_bf16_f32 v90, v90, v91
	v_cvt_pk_bf16_f32 v91, v102, v103
	ds_write_b16 v140, v91 offset:3264
	ds_write_b16_d16_hi v140, v91 offset:3400
	ds_write_b16 v140, v90 offset:7616
	ds_write_b16_d16_hi v140, v90 offset:7752
	s_waitcnt vmcnt(46)
	v_mov_b32_e32 v91, v190
	global_load_ushort v190, v[94:95], off offset:1024
	s_waitcnt vmcnt(46)
	v_mov_b32_e32 v120, v246
	global_load_ushort v246, v[92:93], off offset:512
	s_ashr_i32 s29, s28, 31
	v_lshl_add_u64 v[102:103], v[134:135], 0, s[28:29]
	v_lshl_add_u64 v[104:105], v[102:103], 0, s[26:27]
	s_waitcnt vmcnt(46)
	v_mov_b32_e32 v95, v191
	global_load_ushort v191, v[104:105], off offset:1024
	s_add_i32 s25, s25, s65
	s_mul_i32 s28, s25, 0xe00
	s_ashr_i32 s29, s28, 31
	s_add_i32 s25, s25, s65
	s_nop 0
	v_lshlrev_b32_e32 v91, 16, v91
	v_max_f32_e32 v91, v91, v91
	v_max_f32_e32 v91, 0xc2700000, v91
	v_mul_f32_e32 v91, 0xbfb8aa3b, v91
	v_exp_f32_e32 v94, v91
	s_nop 0
	v_lshlrev_b32_e32 v95, 16, v95
	v_max_f32_e32 v95, v95, v95
	v_max_f32_e32 v95, 0xc2700000, v95
	v_add_f32_e32 v91, 1.0, v94
	v_mul_f32_e32 v95, 0xbfb8aa3b, v95
	v_rcp_f32_e32 v100, v91
	v_exp_f32_e32 v95, v95
	v_fma_f32 v91, v133, v100, v130
	v_add_f32_e32 v98, 1.0, v95
	v_rcp_f32_e32 v101, v98
	v_mul_f32_e32 v98, v99, v91
	v_max_f32_e32 v91, 0xda24260, v98
	v_rcp_f32_e32 v104, v91
	s_waitcnt vmcnt(46)
	v_mov_b32_e32 v91, v211
	global_load_ushort v211, v[92:93], off
	s_nop 0
	s_waitcnt vmcnt(46)
	v_mov_b32_e32 v92, v212
	global_load_ushort v212, v[102:103], off
	v_fma_f32 v105, v133, v101, v130
	v_mul_f32_e32 v99, v98, v105
	v_pk_mul_f32 v[94:95], v[138:139], v[94:95]
	s_nop 0
	v_lshlrev_b32_e32 v93, 16, v92
	v_lshlrev_b32_e32 v92, 16, v91
	v_max_f32_e32 v91, 0xda24260, v99
	v_rcp_f32_e32 v105, v91
	v_pk_mul_f32 v[92:93], v[98:99], v[92:93]
	v_pk_mul_f32 v[94:95], v[94:95], v[100:101]
	v_cvt_pk_bf16_f32 v92, v92, v93
	v_pk_mul_f32 v[94:95], v[94:95], v[104:105]
	s_nop 0
	v_cvt_pk_bf16_f32 v91, v94, v95
	ds_write_b16 v140, v92 offset:3536
	ds_write_b16_d16_hi v140, v92 offset:3672
	ds_write_b16 v140, v91 offset:7888
	ds_write_b16_d16_hi v140, v91 offset:8024
	v_lshl_add_u64 v[92:93], v[134:135], 0, s[28:29]
	v_lshl_add_u64 v[94:95], v[92:93], 0, s[26:27]
	s_waitcnt vmcnt(46)
	v_mov_b32_e32 v121, v248
	global_load_ushort v248, v[102:103], off offset:512
	s_nop 0
	v_mov_b32_e32 v122, v245
	global_load_ushort v245, v[96:97], off offset:512
	s_nop 0
	v_mov_b32_e32 v172, v94
	v_mov_b32_e32 v173, v95
	s_waitcnt vmcnt(47)
	v_mov_b32_e32 v94, v192
	global_load_ushort v192, v[172:173], off offset:1024
	s_mul_i32 s28, s25, 0xe00
	s_ashr_i32 s29, s28, 31
	v_lshl_add_u64 v[100:101], v[134:135], 0, s[28:29]
	v_lshl_add_u64 v[102:103], v[100:101], 0, s[26:27]
	s_waitcnt vmcnt(47)
	v_mov_b32_e32 v123, v249
	global_load_ushort v249, v[92:93], off offset:512
	s_add_i32 s25, s25, s65
	s_mul_i32 s28, s25, 0xe00
	s_ashr_i32 s29, s28, 31
	s_add_i32 s25, s25, s65
	s_nop 0
	v_lshlrev_b32_e32 v94, 16, v94
	v_max_f32_e32 v94, v94, v94
	v_max_f32_e32 v94, 0xc2700000, v94
	v_mul_f32_e32 v94, 0xbfb8aa3b, v94
	v_exp_f32_e32 v94, v94
	s_nop 0
	v_add_f32_e32 v95, 1.0, v94
	v_rcp_f32_e32 v96, v95
	s_waitcnt vmcnt(47)
	v_mov_b32_e32 v95, v193
	global_load_ushort v193, v[102:103], off offset:1024
	s_nop 0
	v_mov_b32_e32 v172, v92
	v_mov_b32_e32 v173, v93
	s_waitcnt vmcnt(47)
	v_mov_b32_e32 v92, v213
	global_load_ushort v213, v[172:173], off
	s_nop 0
	s_waitcnt vmcnt(47)
	v_mov_b32_e32 v93, v214
	global_load_ushort v214, v[100:101], off
	s_waitcnt vmcnt(47)
	v_mov_b32_e32 v132, v250
	global_load_ushort v250, v[100:101], off offset:512
	v_fma_f32 v98, v133, v96, v130
	v_mul_f32_e32 v98, v99, v98
	v_max_f32_e32 v99, 0xda24260, v98
	v_rcp_f32_e32 v102, v99
	s_nop 0
	v_lshlrev_b32_e32 v95, 16, v95
	v_max_f32_e32 v95, v95, v95
	v_max_f32_e32 v95, 0xc2700000, v95
	v_mul_f32_e32 v95, 0xbfb8aa3b, v95
	v_exp_f32_e32 v95, v95
	s_nop 0
	v_lshlrev_b32_e32 v93, 16, v93
	v_lshlrev_b32_e32 v92, 16, v92
	v_add_f32_e32 v97, 1.0, v95
	v_rcp_f32_e32 v97, v97
	s_nop 0
	v_fma_f32 v103, v133, v97, v130
	v_mul_f32_e32 v99, v98, v103
	v_pk_mul_f32 v[104:105], v[98:99], v[92:93]
	v_max_f32_e32 v92, 0xda24260, v99
	v_rcp_f32_e32 v103, v92
	v_pk_mul_f32 v[92:93], v[138:139], v[94:95]
	v_lshl_add_u64 v[94:95], v[134:135], 0, s[28:29]
	v_pk_mul_f32 v[92:93], v[92:93], v[96:97]
	v_lshl_add_u64 v[96:97], v[94:95], 0, s[26:27]
	v_pk_mul_f32 v[92:93], v[92:93], v[102:103]
	s_mul_i32 s28, s25, 0xe00
	v_cvt_pk_bf16_f32 v92, v92, v93
	v_cvt_pk_bf16_f32 v93, v104, v105
	ds_write_b16 v140, v93 offset:3808
	ds_write_b16_d16_hi v140, v93 offset:3944
	ds_write_b16 v140, v92 offset:8160
	ds_write_b16_d16_hi v140, v92 offset:8296
	s_waitcnt vmcnt(47)
	v_mov_b32_e32 v93, v194
	global_load_ushort v194, v[96:97], off offset:1024
	s_waitcnt vmcnt(46)
	v_mov_b32_e32 v159, v251
	global_load_ushort v251, v[94:95], off offset:512
	s_ashr_i32 s29, s28, 31
	v_lshl_add_u64 v[102:103], v[134:135], 0, s[28:29]
	v_lshl_add_u64 v[104:105], v[102:103], 0, s[26:27]
	s_nop 0
	v_mov_b32_e32 v97, v195
	global_load_ushort v195, v[104:105], off offset:1024
	v_lshl_or_b32 v105, v110, 16, v109
	s_cmpk_eq_i32 s24, 0x80
	s_nop 0
	v_lshlrev_b32_e32 v93, 16, v93
	v_max_f32_e32 v93, v93, v93
	v_max_f32_e32 v93, 0xc2700000, v93
	v_mul_f32_e32 v93, 0xbfb8aa3b, v93
	v_exp_f32_e32 v96, v93
	s_nop 0
	v_lshlrev_b32_e32 v97, 16, v97
	v_max_f32_e32 v97, v97, v97
	v_max_f32_e32 v97, 0xc2700000, v97
	v_add_f32_e32 v93, 1.0, v96
	v_rcp_f32_e32 v100, v93
	v_mul_f32_e32 v97, 0xbfb8aa3b, v97
	v_exp_f32_e32 v97, v97
	v_fma_f32 v93, v133, v100, v130
	v_mul_f32_e32 v106, v99, v93
	v_add_f32_e32 v98, 1.0, v97
	v_max_f32_e32 v93, 0xda24260, v106
	v_rcp_f32_e32 v101, v98
	v_rcp_f32_e32 v98, v93
	s_waitcnt vmcnt(47)
	v_mov_b32_e32 v93, v215
	global_load_ushort v215, v[94:95], off
	s_nop 0
	s_waitcnt vmcnt(47)
	v_mov_b32_e32 v94, v216
	global_load_ushort v216, v[102:103], off
	v_pk_mul_f32 v[96:97], v[138:139], v[96:97]
	v_fma_f32 v104, v133, v101, v130
	v_mul_f32_e32 v107, v106, v104
	v_pk_mul_f32 v[96:97], v[96:97], v[100:101]
	v_lshl_or_b32 v101, v117, 16, v116
	v_lshl_or_b32 v100, v118, 16, v115
	v_lshl_or_b32 v104, v108, 16, v89
	v_cvt_pk_bf16_f32 v115, v30, v31
	s_nop 0
	v_lshlrev_b32_e32 v95, 16, v94
	v_lshlrev_b32_e32 v94, 16, v93
	v_pk_mul_f32 v[94:95], v[106:107], v[94:95]
	v_max_f32_e32 v93, 0xda24260, v107
	v_cvt_pk_bf16_f32 v94, v94, v95
	s_waitcnt vmcnt(47)
	v_mov_b32_e32 v95, v252
	global_load_ushort v252, v[102:103], off offset:512
	v_rcp_f32_e32 v99, v93
	v_lshl_or_b32 v103, v88, 16, v87
	v_lshl_or_b32 v102, v86, 16, v85
	v_pk_mul_f32 v[96:97], v[96:97], v[98:99]
	s_nop 0
	v_cvt_pk_bf16_f32 v93, v96, v97
	ds_write_b16 v140, v94 offset:4080
	ds_write_b16_d16_hi v140, v94 offset:4216
	ds_write_b16 v140, v93 offset:8432
	ds_write_b16_d16_hi v140, v93 offset:8568
	v_lshl_or_b32 v96, v132, 16, v123
	v_lshl_or_b32 v94, v122, 16, v119
	v_lshl_or_b32 v99, v113, 16, v112
	v_lshl_or_b32 v98, v114, 16, v111
	v_add_u32_e32 v112, v145, v142
	v_add_u32_e32 v116, 0x3800, v112
	v_cvt_pk_bf16_f32 v113, v14, v15
	v_cvt_pk_bf16_f32 v114, v28, v29
	s_nop 0
	v_lshl_or_b32 v97, v95, 16, v159
	v_lshl_or_b32 v95, v121, 16, v120
	ds_write_b128 v141, v[68:71] offset:8704
	ds_write_b128 v141, v[80:83] offset:12800
	ds_write_b128 v141, v[72:75] offset:8720
	ds_write_b128 v141, v[102:105] offset:12816
	ds_write_b128 v141, v[76:79] offset:8736
	ds_write_b128 v141, v[98:101] offset:12832
	ds_write_b128 v141, v[90:93] offset:8752
	ds_write_b128 v141, v[94:97] offset:12848
	ds_write_b32 v151, v107 offset:16896
	s_waitcnt lgkmcnt(0)
	ds_read2_b64 v[84:87], v152 offset1:4
	ds_read2_b64 v[68:71], v0 offset0:32 offset1:36
	ds_read2_b64 v[96:99], v152 offset0:8 offset1:12
	ds_read2_b64 v[72:75], v0 offset0:40 offset1:44
	v_add_u32_e32 v0, 0x800, v152
	ds_read2_b64 v[100:103], v0 offset0:16 offset1:20
	ds_read2_b64 v[76:79], v1 offset0:48 offset1:52
	ds_read2_b64 v[104:107], v0 offset0:24 offset1:28
	ds_read2_b64 v[80:83], v1 offset0:56 offset1:60
	s_waitcnt lgkmcnt(6)
	v_mfma_f32_16x16x32_bf16 v[88:91], v[68:71], v[84:87], 0
	v_cvt_pk_bf16_f32 v92, v40, v41
	v_cvt_pk_bf16_f32 v93, v42, v43
	v_cvt_pk_bf16_f32 v94, v56, v57
	s_waitcnt lgkmcnt(3)
	v_mfma_f32_16x16x32_bf16 v[68:71], v[68:71], v[100:103], 0
	v_cvt_pk_bf16_f32 v95, v58, v59
	s_waitcnt lgkmcnt(2)
	v_mfma_f32_16x16x32_bf16 v[76:79], v[76:79], v[100:103], 0
	v_mfma_f32_16x16x32_bf16 v[88:91], v[72:75], v[96:99], v[88:91]
	s_waitcnt lgkmcnt(1)
	v_mfma_f32_16x16x32_bf16 v[68:71], v[72:75], v[104:107], v[68:71]
	s_waitcnt lgkmcnt(0)
	v_mfma_f32_16x16x32_bf16 v[76:79], v[80:83], v[104:107], v[76:79]
	s_nop 3
	v_cndmask_b32_e64 v1, v91, 0, vcc
	v_cndmask_b32_e64 v3, v90, 0, s[42:43]
	v_cndmask_b32_e64 v0, v89, 0, s[40:41]
	v_cndmask_b32_e64 v80, v88, 0, s[38:39]
	v_add_u32_e32 v88, 0x3000, v112
	v_cvt_pk_bf16_f32 v0, v80, v0
	v_cvt_pk_bf16_f32 v1, v3, v1
	v_mov_b32_e32 v3, v2
	v_cvt_pk_bf16_f32 v108, v68, v69
	v_cvt_pk_bf16_f32 v109, v70, v71
	ds_read2_b64 v[68:71], v88 offset0:64 offset1:68
	v_cndmask_b32_e64 v79, v79, 0, vcc
	v_cndmask_b32_e64 v78, v78, 0, s[42:43]
	v_cndmask_b32_e64 v77, v77, 0, s[40:41]
	v_cndmask_b32_e64 v76, v76, 0, s[38:39]
	v_cvt_pk_bf16_f32 v110, v76, v77
	v_cvt_pk_bf16_f32 v111, v78, v79
	s_waitcnt lgkmcnt(0)
	v_mfma_f32_16x16x32_bf16 v[72:75], v[0:3], v[68:71], 0
	v_cvt_pk_bf16_f32 v76, v4, v5
	v_cvt_pk_bf16_f32 v77, v6, v7
	v_cvt_pk_bf16_f32 v78, v20, v21
	v_mfma_f32_16x16x32_bf16 v[68:71], v[108:111], v[68:71], 0
	v_cvt_pk_bf16_f32 v79, v22, v23
	v_cvt_pk_bf16_f32 v89, v10, v11
	v_cvt_pk_bf16_f32 v90, v24, v25
	v_mfma_f32_16x16x32_bf16 v[72:75], v[84:87], v[76:79], v[72:75]
	v_cvt_pk_bf16_f32 v91, v26, v27
	v_cvt_pk_bf16_f32 v112, v12, v13
	v_mfma_f32_16x16x32_bf16 v[68:71], v[100:103], v[76:79], v[68:71]
	v_cvt_pk_bf16_f32 v76, v36, v37
	v_cvt_pk_bf16_f32 v77, v38, v39
	v_cvt_pk_bf16_f32 v78, v52, v53
	v_cvt_pk_bf16_f32 v79, v54, v55
	s_nop 1
	v_mfma_f32_16x16x32_bf16 v[80:83], v[96:99], v[76:79], v[72:75]
	s_nop 2
	ds_read2_b64 v[72:75], v88 offset0:192 offset1:196
	v_mfma_f32_16x16x32_bf16 v[68:71], v[104:107], v[76:79], v[68:71]
	v_cvt_pk_bf16_f32 v88, v8, v9
	s_waitcnt lgkmcnt(0)
	v_mfma_f32_16x16x32_bf16 v[76:79], v[0:3], v[72:75], 0
	v_mfma_f32_16x16x32_bf16 v[72:75], v[108:111], v[72:75], 0
	v_mfma_f32_16x16x32_bf16 v[76:79], v[84:87], v[88:91], v[76:79]
	v_mfma_f32_16x16x32_bf16 v[72:75], v[100:103], v[88:91], v[72:75]
	v_mfma_f32_16x16x32_bf16 v[88:91], v[96:99], v[92:95], v[76:79]
	s_nop 5
	ds_read2_b64 v[76:79], v116 offset0:64 offset1:68
	v_mfma_f32_16x16x32_bf16 v[72:75], v[104:107], v[92:95], v[72:75]
	s_waitcnt lgkmcnt(0)
	v_mfma_f32_16x16x32_bf16 v[92:95], v[0:3], v[76:79], 0
	v_mfma_f32_16x16x32_bf16 v[76:79], v[108:111], v[76:79], 0
	v_mfma_f32_16x16x32_bf16 v[92:95], v[84:87], v[112:115], v[92:95]
	v_mfma_f32_16x16x32_bf16 v[76:79], v[100:103], v[112:115], v[76:79]
	v_cvt_pk_bf16_f32 v112, v44, v45
	v_cvt_pk_bf16_f32 v113, v46, v47
	v_cvt_pk_bf16_f32 v114, v60, v61
	v_cvt_pk_bf16_f32 v115, v62, v63
	s_nop 1
	v_mfma_f32_16x16x32_bf16 v[92:95], v[96:99], v[112:115], v[92:95]
	v_mfma_f32_16x16x32_bf16 v[76:79], v[104:107], v[112:115], v[76:79]
	ds_read2_b64 v[112:115], v116 offset0:192 offset1:196
	s_waitcnt lgkmcnt(0)
	v_mfma_f32_16x16x32_bf16 v[116:119], v[0:3], v[112:115], 0
	v_add_u32_e32 v0, v146, v143
	v_mfma_f32_16x16x32_bf16 v[108:111], v[108:111], v[112:115], 0
	v_cvt_pk_bf16_f32 v112, v16, v17
	v_cvt_pk_bf16_f32 v113, v18, v19
	v_cvt_pk_bf16_f32 v114, v32, v33
	v_cvt_pk_bf16_f32 v115, v34, v35
	s_nop 1
	v_mfma_f32_16x16x32_bf16 v[84:87], v[84:87], v[112:115], v[116:119]
	v_mfma_f32_16x16x32_bf16 v[100:103], v[100:103], v[112:115], v[108:111]
	s_nop 2
	v_cvt_pk_bf16_f32 v108, v48, v49
	v_cvt_pk_bf16_f32 v109, v50, v51
	v_cvt_pk_bf16_f32 v110, v64, v65
	v_cvt_pk_bf16_f32 v111, v66, v67
	s_nop 1
	v_mfma_f32_16x16x32_bf16 v[96:99], v[96:99], v[108:111], v[84:87]
	v_mfma_f32_16x16x32_bf16 v[84:87], v[104:107], v[108:111], v[100:103]
	ds_read_b128 v[160:163], v0 offset:8704
	ds_read_b128 v[116:119], v0 offset:12800
	ds_read_b128 v[164:167], v0 offset:9728
	ds_read_b128 v[112:115], v0 offset:13824
	ds_read_b128 v[120:123], v0 offset:10752
	ds_read_b128 v[108:111], v0 offset:14848
	ds_read_b128 v[100:103], v0 offset:11776
	ds_read_b128 v[104:107], v0 offset:15872
	ds_read_b128 v[168:171], v146 offset:16896
	v_cvt_pk_bf16_f32 v0, v80, s0
	s_waitcnt lgkmcnt(7)
	v_mfma_f32_16x16x32_bf16 v[4:7], v[160:163], v[116:119], v[4:7]
	s_waitcnt lgkmcnt(5)
	v_mfma_f32_16x16x32_bf16 v[8:11], v[160:163], v[112:115], v[8:11]
	s_waitcnt lgkmcnt(3)
	v_mfma_f32_16x16x32_bf16 v[12:15], v[160:163], v[108:111], v[12:15]
	s_waitcnt lgkmcnt(0)
	s_nop 2
	v_pk_mul_f32 v[6:7], v[170:171], v[6:7]
	v_pk_mul_f32 v[4:5], v[168:169], v[4:5]
	v_pk_mul_f32 v[10:11], v[170:171], v[10:11]
	v_mfma_f32_16x16x32_bf16 v[16:19], v[160:163], v[104:107], v[16:19]
	ds_read_b128 v[160:163], v146 offset:16960
	v_pk_mul_f32 v[8:9], v[168:169], v[8:9]
	v_pk_mul_f32 v[14:15], v[170:171], v[14:15]
	v_mfma_f32_16x16x32_bf16 v[20:23], v[164:167], v[116:119], v[20:23]
	v_mul_f32_e64 v12, v168, v12
	v_mul_f32_e64 v13, v169, v13
	s_nop 1
	v_pk_mul_f32 v[18:19], v[170:171], v[18:19]
	v_pk_mul_f32 v[16:17], v[168:169], v[16:17]
	v_mfma_f32_16x16x32_bf16 v[24:27], v[164:167], v[112:115], v[24:27]
	v_mfma_f32_16x16x32_bf16 v[28:31], v[164:167], v[108:111], v[28:31]
	v_mfma_f32_16x16x32_bf16 v[32:35], v[164:167], v[104:107], v[32:35]
	v_mfma_f32_16x16x32_bf16 v[36:39], v[120:123], v[116:119], v[36:39]
	v_mfma_f32_16x16x32_bf16 v[40:43], v[120:123], v[112:115], v[40:43]
	v_mfma_f32_16x16x32_bf16 v[44:47], v[120:123], v[108:111], v[44:47]
	v_mfma_f32_16x16x32_bf16 v[48:51], v[120:123], v[104:107], v[48:51]
	ds_read_b128 v[120:123], v146 offset:17088
	s_waitcnt lgkmcnt(1)
	v_pk_mul_f32 v[22:23], v[162:163], v[22:23]
	v_pk_mul_f32 v[20:21], v[160:161], v[20:21]
	v_pk_mul_f32 v[26:27], v[162:163], v[26:27]
	v_pk_mul_f32 v[24:25], v[160:161], v[24:25]
	v_pk_mul_f32 v[30:31], v[162:163], v[30:31]
	v_pk_mul_f32 v[28:29], v[160:161], v[28:29]
	v_pk_mul_f32 v[34:35], v[162:163], v[34:35]
	v_pk_mul_f32 v[32:33], v[160:161], v[32:33]
	ds_read_b128 v[160:163], v146 offset:17024
	ds_write_b16 v153, v0
	v_cvt_pk_bf16_f32 v0, v88, s0
	ds_write_b16 v153, v0 offset:32
	v_cvt_pk_bf16_f32 v0, v92, s0
	ds_write_b16 v153, v0 offset:64
	v_cvt_pk_bf16_f32 v0, v96, s0
	ds_write_b16 v153, v0 offset:96
	v_cvt_pk_bf16_f32 v0, v81, s0
	ds_write_b16 v154, v0
	v_cvt_pk_bf16_f32 v0, v89, s0
	ds_write_b16 v154, v0 offset:32
	v_cvt_pk_bf16_f32 v0, v93, s0
	ds_write_b16 v154, v0 offset:64
	v_cvt_pk_bf16_f32 v0, v97, s0
	ds_write_b16 v154, v0 offset:96
	v_cvt_pk_bf16_f32 v0, v82, s0
	ds_write_b16 v154, v0 offset:136
	v_cvt_pk_bf16_f32 v0, v90, s0
	ds_write_b16 v154, v0 offset:168
	v_cvt_pk_bf16_f32 v0, v94, s0
	ds_write_b16 v154, v0 offset:200
	v_cvt_pk_bf16_f32 v0, v98, s0
	ds_write_b16 v154, v0 offset:232
	v_cvt_pk_bf16_f32 v0, v83, s0
	ds_write_b16 v154, v0 offset:272
	v_cvt_pk_bf16_f32 v0, v91, s0
	ds_write_b16 v154, v0 offset:304
	v_cvt_pk_bf16_f32 v0, v95, s0
	ds_write_b16 v154, v0 offset:336
	v_cvt_pk_bf16_f32 v0, v99, s0
	ds_write_b16 v154, v0 offset:368
	v_cvt_pk_bf16_f32 v0, v68, s0
	ds_write_b16 v154, v0 offset:2040
	v_cvt_pk_bf16_f32 v0, v72, s0
	ds_write_b16 v154, v0 offset:2072
	v_cvt_pk_bf16_f32 v0, v76, s0
	ds_write_b16 v154, v0 offset:2104
	v_cvt_pk_bf16_f32 v0, v84, s0
	ds_write_b16 v154, v0 offset:2136
	v_cvt_pk_bf16_f32 v0, v69, s0
	ds_write_b16 v154, v0 offset:2176
	v_cvt_pk_bf16_f32 v0, v73, s0
	ds_write_b16 v154, v0 offset:2208
	v_cvt_pk_bf16_f32 v0, v77, s0
	ds_write_b16 v154, v0 offset:2240
	v_cvt_pk_bf16_f32 v0, v85, s0
	ds_write_b16 v154, v0 offset:2272
	v_cvt_pk_bf16_f32 v0, v70, s0
	ds_write_b16 v154, v0 offset:2312
	v_cvt_pk_bf16_f32 v0, v74, s0
	ds_write_b16 v154, v0 offset:2344
	v_cvt_pk_bf16_f32 v0, v78, s0
	ds_write_b16 v154, v0 offset:2376
	v_cvt_pk_bf16_f32 v0, v86, s0
	ds_write_b16 v154, v0 offset:2408
	v_cvt_pk_bf16_f32 v0, v71, s0
	ds_write_b16 v154, v0 offset:2448
	v_cvt_pk_bf16_f32 v0, v75, s0
	ds_write_b16 v154, v0 offset:2480
	v_cvt_pk_bf16_f32 v0, v79, s0
	ds_write_b16 v154, v0 offset:2512
	v_cvt_pk_bf16_f32 v0, v87, s0
	ds_write_b16 v154, v0 offset:2544
	s_waitcnt lgkmcnt(0)
	ds_read2_b64 v[68:71], v155 offset1:1
	v_add_u32_e32 v0, s3, v147
	v_ashrrev_i32_e32 v1, 31, v0
	v_lshl_add_u64 v[0:1], s[56:57], 0, v[0:1]
	v_lshlrev_b64 v[0:1], 9, v[0:1]
	v_lshl_add_u64 v[0:1], v[136:137], 0, v[0:1]
	s_waitcnt lgkmcnt(0)
	global_store_dwordx4 v[0:1], v[68:71], off
	ds_read2_b64 v[68:71], v156 offset1:1
	v_add_u32_e32 v0, s3, v148
	v_ashrrev_i32_e32 v1, 31, v0
	v_lshl_add_u64 v[0:1], s[56:57], 0, v[0:1]
	v_lshlrev_b64 v[0:1], 9, v[0:1]
	v_lshl_add_u64 v[0:1], v[136:137], 0, v[0:1]
	s_waitcnt lgkmcnt(0)
	global_store_dwordx4 v[0:1], v[68:71], off
	ds_read2_b64 v[68:71], v157 offset1:1
	v_add_u32_e32 v0, s3, v149
	v_ashrrev_i32_e32 v1, 31, v0
	v_lshl_add_u64 v[0:1], s[56:57], 0, v[0:1]
	v_lshlrev_b64 v[0:1], 9, v[0:1]
	v_lshl_add_u64 v[0:1], v[136:137], 0, v[0:1]
	s_waitcnt lgkmcnt(0)
	global_store_dwordx4 v[0:1], v[68:71], off
	ds_read2_b64 v[68:71], v158 offset1:1
	v_add_u32_e32 v0, s3, v150
	v_ashrrev_i32_e32 v1, 31, v0
	v_lshl_add_u64 v[0:1], s[56:57], 0, v[0:1]
	v_lshlrev_b64 v[0:1], 9, v[0:1]
	v_mfma_f32_16x16x32_bf16 v[52:55], v[100:103], v[116:119], v[52:55]
	v_lshl_add_u64 v[0:1], v[136:137], 0, v[0:1]
	s_waitcnt lgkmcnt(0)
	global_store_dwordx4 v[0:1], v[68:71], off
	s_waitcnt lgkmcnt(0)
	v_mfma_f32_16x16x32_bf16 v[56:59], v[100:103], v[112:115], v[56:59]
	v_mul_f32_e64 v38, v162, v38
	v_mul_f32_e64 v39, v163, v39
	v_pk_mul_f32 v[36:37], v[160:161], v[36:37]
	v_pk_mul_f32 v[42:43], v[162:163], v[42:43]
	v_mfma_f32_16x16x32_bf16 v[60:63], v[100:103], v[108:111], v[60:63]
	v_mul_f32_e64 v40, v160, v40
	v_mul_f32_e64 v41, v161, v41
	v_pk_mul_f32 v[46:47], v[162:163], v[46:47]
	v_pk_mul_f32 v[44:45], v[160:161], v[44:45]
	v_mfma_f32_16x16x32_bf16 v[64:67], v[100:103], v[104:107], v[64:67]
	v_mul_f32_e64 v50, v162, v50
	v_mul_f32_e64 v51, v163, v51
	v_pk_mul_f32 v[48:49], v[160:161], v[48:49]
	v_pk_mul_f32 v[54:55], v[122:123], v[54:55]
	v_pk_mul_f32 v[52:53], v[120:121], v[52:53]
	v_pk_mul_f32 v[58:59], v[122:123], v[58:59]
	v_pk_mul_f32 v[56:57], v[120:121], v[56:57]
	v_pk_mul_f32 v[62:63], v[122:123], v[62:63]
	v_pk_mul_f32 v[60:61], v[120:121], v[60:61]
	v_pk_mul_f32 v[66:67], v[122:123], v[66:67]
	v_pk_mul_f32 v[64:65], v[120:121], v[64:65]
	s_cbranch_scc0 .LBB0_687
	s_lshl_b32 s3, s69, 7
	s_waitcnt vmcnt(0)
	s_barrier
	s_load_dwordx2 s[24:25], s[44:45], 0x48
	s_and_b32 s3, s3, 0x3f80
	v_or_b32_e32 v1, s3, v144
	v_and_b32_e32 v3, 64, v204
	v_or_b32_e32 v134, s56, v1
	v_xor_b32_e32 v1, 1, v204
	v_add_u32_e32 v3, 64, v3
	s_lshl_b64 s[28:29], s[48:49], 2
	v_cmp_lt_i32_e32 vcc, v1, v3
	s_waitcnt lgkmcnt(0)
	s_add_u32 s24, s24, s28
	s_addc_u32 s25, s25, s29
	v_cndmask_b32_e32 v130, v204, v1, vcc
	v_xor_b32_e32 v1, 2, v204
	s_lshl_b32 s28, s55, 2
	v_cmp_lt_i32_e32 vcc, v1, v3
	s_add_u32 s24, s24, s28
	s_addc_u32 s25, s25, 0
	v_cndmask_b32_e32 v131, v204, v1, vcc
	v_xor_b32_e32 v1, 4, v204
	v_lshlrev_b32_e32 v0, 2, v124
	v_mov_b32_e32 v135, s57
	s_mov_b32 s55, s27
	v_cmp_lt_i32_e32 vcc, v1, v3
	v_lshl_add_u64 v[12:13], v[126:127], 0, s[54:55]
	v_lshl_add_u64 v[14:15], v[128:129], 0, s[54:55]
	v_cndmask_b32_e32 v3, v204, v1, vcc
	global_load_dwordx4 v[4:7], v0, s[24:25] offset:16
	global_load_dwordx4 v[8:11], v0, s[24:25]
	v_lshlrev_b64 v[0:1], 9, v[134:135]
	v_lshl_add_u64 v[16:17], v[12:13], 0, v[0:1]
	v_lshl_add_u64 v[0:1], v[14:15], 0, v[0:1]
	global_load_dwordx4 v[100:103], v[16:17], off
	global_load_dwordx4 v[104:107], v[0:1], off
	v_mov_b64_e32 v[0:1], s[50:51]
	v_mad_u64_u32 v[0:1], s[24:25], v134, s83, v[0:1]
	v_mad_i32_i24 v1, s57, v243, v1
	v_lshl_add_u64 v[16:17], v[0:1], 0, s[54:55]
	v_lshlrev_b32_e32 v0, 1, v124
	v_mov_b32_e32 v1, v2
	v_lshl_add_u64 v[122:123], v[16:17], 0, v[0:1]
	global_load_dwordx4 v[96:99], v[122:123], off offset:2048
	v_or_b32_e32 v120, 8, v134
	v_mov_b32_e32 v121, s57
	v_lshlrev_b64 v[16:17], 9, v[120:121]
	v_lshl_add_u64 v[18:19], v[12:13], 0, v[16:17]
	v_lshl_add_u64 v[16:17], v[14:15], 0, v[16:17]
	s_movk_i32 s3, 0x7000
	global_load_dwordx4 v[92:95], v[18:19], off
	global_load_dwordx4 v[88:91], v[16:17], off
	v_add_co_u32_e32 v16, vcc, s3, v122
	v_or_b32_e32 v118, 16, v134
	s_nop 0
	v_addc_co_u32_e32 v17, vcc, 0, v123, vcc
	v_mov_b32_e32 v119, s57
	global_load_dwordx4 v[84:87], v[16:17], off offset:2048
	v_lshlrev_b64 v[16:17], 9, v[118:119]
	v_lshl_add_u64 v[18:19], v[12:13], 0, v[16:17]
	v_lshl_add_u64 v[16:17], v[14:15], 0, v[16:17]
	s_mov_b32 s3, 0xe000
	global_load_dwordx4 v[76:79], v[18:19], off
	global_load_dwordx4 v[80:83], v[16:17], off
	v_add_co_u32_e32 v16, vcc, s3, v122
	v_or_b32_e32 v116, 24, v134
	s_nop 0
	v_addc_co_u32_e32 v17, vcc, 0, v123, vcc
	v_mov_b32_e32 v117, s57
	global_load_dwordx4 v[72:75], v[16:17], off offset:2048
	v_lshlrev_b64 v[16:17], 9, v[116:117]
	v_lshl_add_u64 v[18:19], v[12:13], 0, v[16:17]
	v_lshl_add_u64 v[16:17], v[14:15], 0, v[16:17]
	s_mov_b32 s3, 0x15000
	global_load_dwordx4 v[68:71], v[18:19], off
	global_load_dwordx4 v[64:67], v[16:17], off
	v_add_co_u32_e32 v16, vcc, s3, v122
	v_or_b32_e32 v114, 32, v134
	s_nop 0
	v_addc_co_u32_e32 v17, vcc, 0, v123, vcc
	v_mov_b32_e32 v115, s57
	global_load_dwordx4 v[60:63], v[16:17], off offset:2048
	v_lshlrev_b64 v[16:17], 9, v[114:115]
	v_lshl_add_u64 v[18:19], v[12:13], 0, v[16:17]
	v_lshl_add_u64 v[16:17], v[14:15], 0, v[16:17]
	s_mov_b32 s3, 0x1c000
	global_load_dwordx4 v[52:55], v[18:19], off
	global_load_dwordx4 v[56:59], v[16:17], off
	v_add_co_u32_e32 v16, vcc, s3, v122
	v_or_b32_e32 v112, 40, v134
	s_nop 0
	v_addc_co_u32_e32 v17, vcc, 0, v123, vcc
	v_mov_b32_e32 v113, s57
	global_load_dwordx4 v[48:51], v[16:17], off offset:2048
	v_lshlrev_b64 v[16:17], 9, v[112:113]
	v_lshl_add_u64 v[18:19], v[12:13], 0, v[16:17]
	v_lshl_add_u64 v[16:17], v[14:15], 0, v[16:17]
	s_mov_b32 s3, 0x23000
	global_load_dwordx4 v[44:47], v[18:19], off
	global_load_dwordx4 v[40:43], v[16:17], off
	v_add_co_u32_e32 v16, vcc, s3, v122
	v_or_b32_e32 v110, 48, v134
	s_nop 0
	v_addc_co_u32_e32 v17, vcc, 0, v123, vcc
	v_mov_b32_e32 v111, s57
	global_load_dwordx4 v[36:39], v[16:17], off offset:2048
	v_lshlrev_b64 v[16:17], 9, v[110:111]
	v_lshl_add_u64 v[18:19], v[12:13], 0, v[16:17]
	v_lshl_add_u64 v[16:17], v[14:15], 0, v[16:17]
	s_mov_b32 s3, 0x2a000
	v_or_b32_e32 v108, 56, v134
	v_mov_b32_e32 v109, s57
	global_load_dwordx4 v[28:31], v[18:19], off
	global_load_dwordx4 v[32:35], v[16:17], off
	v_add_co_u32_e32 v16, vcc, s3, v122
	v_lshlrev_b64 v[20:21], 9, v[108:109]
	s_nop 0
	v_addc_co_u32_e32 v17, vcc, 0, v123, vcc
	v_lshl_add_u64 v[12:13], v[12:13], 0, v[20:21]
	global_load_dwordx4 v[24:27], v[16:17], off offset:2048
	s_mov_b32 s3, 0x31000
	global_load_dwordx4 v[16:19], v[12:13], off
	v_lshl_add_u64 v[12:13], v[14:15], 0, v[20:21]
	global_load_dwordx4 v[20:23], v[12:13], off
	v_add_co_u32_e32 v12, vcc, s3, v122
	v_lshlrev_b32_e32 v146, 2, v130
	s_nop 0
	v_addc_co_u32_e32 v13, vcc, 0, v123, vcc
	v_lshlrev_b32_e32 v145, 2, v131
	s_waitcnt vmcnt(22)
	v_lshlrev_b32_e32 v122, 16, v103
	v_and_b32_e32 v123, 0xffff0000, v103
	s_waitcnt vmcnt(21)
	v_lshlrev_b32_e32 v130, 16, v107
	v_and_b32_e32 v131, 0xffff0000, v107
	v_pk_add_f32 v[122:123], v[122:123], v[130:131]
	v_lshlrev_b32_e32 v130, 16, v102
	v_and_b32_e32 v131, 0xffff0000, v102
	v_lshlrev_b32_e32 v102, 16, v106
	v_and_b32_e32 v103, 0xffff0000, v106
	v_pk_add_f32 v[102:103], v[130:131], v[102:103]
	v_mov_b32_e32 v130, v123
	v_mov_b32_e32 v131, v103
	v_mov_b32_e32 v106, v122
	v_mov_b32_e32 v107, v102
	v_pk_mul_f32 v[130:131], v[130:131], v[130:131]
	v_lshlrev_b32_e32 v136, 16, v105
	v_pk_fma_f32 v[132:133], v[106:107], v[106:107], v[130:131]
	s_waitcnt vmcnt(20)
	v_lshlrev_b32_e32 v106, 16, v98
	v_and_b32_e32 v107, 0xffff0000, v98
	v_max_f32_e32 v98, v106, v106
	v_max_f32_e32 v98, 0xc2700000, v98
	v_mul_f32_e32 v98, 0xbfb8aa3b, v98
	v_exp_f32_e32 v98, v98
	v_and_b32_e32 v137, 0xffff0000, v105
	s_waitcnt vmcnt(18)
	v_lshlrev_b32_e32 v140, 16, v91
	v_and_b32_e32 v141, 0xffff0000, v91
	v_add_f32_e32 v98, 1.0, v98
	v_rcp_f32_e32 v130, v98
	v_max_f32_e32 v98, v107, v107
	v_max_f32_e32 v98, 0xc2700000, v98
	v_mul_f32_e32 v98, 0xbfb8aa3b, v98
	v_exp_f32_e32 v98, v98
	v_lshlrev_b32_e32 v142, 16, v89
	v_and_b32_e32 v143, 0xffff0000, v89
	v_lshlrev_b32_e32 v3, 2, v3
	v_add_f32_e32 v98, 1.0, v98
	v_rcp_f32_e32 v131, v98
	s_mov_b32 s24, 0x358637bd
	global_load_dwordx4 v[12:15], v[12:13], off offset:2048
	s_add_i32 s68, s68, s75
	v_pk_mul_f32 v[106:107], v[130:131], v[106:107]
	v_lshlrev_b32_e32 v130, 16, v101
	v_and_b32_e32 v131, 0xffff0000, v101
	v_pk_add_f32 v[130:131], v[130:131], v[136:137]
	v_lshlrev_b32_e32 v136, 16, v97
	v_and_b32_e32 v137, 0xffff0000, v97
	v_max_f32_e32 v97, v136, v136
	v_max_f32_e32 v97, 0xc2700000, v97
	v_mul_f32_e32 v97, 0xbfb8aa3b, v97
	v_exp_f32_e32 v97, v97
	v_and_b32_e32 v101, 0xffff0000, v104
	v_mov_b32_e32 v105, v130
	s_add_i32 s67, s67, s22
	v_add_f32_e32 v97, 1.0, v97
	v_rcp_f32_e32 v138, v97
	v_max_f32_e32 v97, v137, v137
	v_max_f32_e32 v97, 0xc2700000, v97
	v_mul_f32_e32 v97, 0xbfb8aa3b, v97
	v_exp_f32_e32 v97, v97
	s_cmpk_gt_i32 s68, 0x3ff
	v_add_f32_e32 v97, 1.0, v97
	v_rcp_f32_e32 v139, v97
	s_nop 0
	v_pk_mul_f32 v[136:137], v[138:139], v[136:137]
	v_lshlrev_b32_e32 v138, 16, v100
	v_and_b32_e32 v139, 0xffff0000, v100
	v_lshlrev_b32_e32 v100, 16, v104
	v_pk_add_f32 v[100:101], v[138:139], v[100:101]
	v_mov_b32_e32 v139, v131
	v_mov_b32_e32 v138, v101
	v_mov_b32_e32 v104, v100
	v_pk_mul_f32 v[138:139], v[138:139], v[138:139]
	s_nop 0
	v_pk_fma_f32 v[138:139], v[104:105], v[104:105], v[138:139]
	v_lshlrev_b32_e32 v104, 16, v96
	v_and_b32_e32 v105, 0xffff0000, v96
	v_max_f32_e32 v96, v104, v104
	v_max_f32_e32 v97, v105, v105
	v_max_f32_e32 v96, 0xc2700000, v96
	v_max_f32_e32 v97, 0xc2700000, v97
	v_mul_f32_e32 v96, 0xbfb8aa3b, v96
	v_mul_f32_e32 v97, 0xbfb8aa3b, v97
	v_exp_f32_e32 v96, v96
	v_exp_f32_e32 v97, v97
	v_add_f32_e32 v96, 1.0, v96
	v_add_f32_e32 v97, 1.0, v97
	v_rcp_f32_e32 v96, v96
	v_rcp_f32_e32 v97, v97
	s_nop 0
	v_pk_mul_f32 v[104:105], v[96:97], v[104:105]
	v_lshlrev_b32_e32 v96, 16, v99
	v_and_b32_e32 v97, 0xffff0000, v99
	v_max_f32_e32 v98, v96, v96
	v_max_f32_e32 v99, v97, v97
	v_max_f32_e32 v98, 0xc2700000, v98
	v_max_f32_e32 v99, 0xc2700000, v99
	v_mul_f32_e32 v98, 0xbfb8aa3b, v98
	v_mul_f32_e32 v99, 0xbfb8aa3b, v99
	v_exp_f32_e32 v98, v98
	v_exp_f32_e32 v99, v99
	v_add_f32_e32 v98, 1.0, v98
	v_add_f32_e32 v99, 1.0, v99
	v_rcp_f32_e32 v98, v98
	v_rcp_f32_e32 v99, v99
	s_nop 0
	v_pk_mul_f32 v[98:99], v[98:99], v[96:97]
	v_lshlrev_b64 v[96:97], 11, v[134:135]
	v_lshl_add_u64 v[96:97], s[46:47], 0, v[96:97]
	v_lshl_add_u64 v[96:97], v[96:97], 0, s[54:55]
	v_lshl_add_u64 v[134:135], v[96:97], 0, v[0:1]
	v_lshlrev_b32_e32 v96, 16, v95
	v_and_b32_e32 v97, 0xffff0000, v95
	v_pk_add_f32 v[96:97], v[96:97], v[140:141]
	v_lshlrev_b32_e32 v140, 16, v94
	v_and_b32_e32 v141, 0xffff0000, v94
	v_lshlrev_b32_e32 v94, 16, v90
	v_and_b32_e32 v95, 0xffff0000, v90
	v_pk_add_f32 v[90:91], v[140:141], v[94:95]
	v_mov_b32_e32 v140, v97
	v_mov_b32_e32 v141, v91
	v_mov_b32_e32 v94, v96
	v_mov_b32_e32 v95, v90
	v_pk_mul_f32 v[140:141], v[140:141], v[140:141]
	s_nop 0
	v_pk_fma_f32 v[148:149], v[94:95], v[94:95], v[140:141]
	s_waitcnt vmcnt(18)
	v_lshlrev_b32_e32 v94, 16, v86
	v_and_b32_e32 v95, 0xffff0000, v86
	v_max_f32_e32 v86, v94, v94
	v_max_f32_e32 v86, 0xc2700000, v86
	v_mul_f32_e32 v86, 0xbfb8aa3b, v86
	v_exp_f32_e32 v86, v86
	s_nop 0
	v_add_f32_e32 v86, 1.0, v86
	v_rcp_f32_e32 v140, v86
	v_max_f32_e32 v86, v95, v95
	v_max_f32_e32 v86, 0xc2700000, v86
	v_mul_f32_e32 v86, 0xbfb8aa3b, v86
	v_exp_f32_e32 v86, v86
	s_nop 0
	v_add_f32_e32 v86, 1.0, v86
	v_rcp_f32_e32 v141, v86
	s_nop 0
	v_pk_mul_f32 v[94:95], v[140:141], v[94:95]
	v_lshlrev_b32_e32 v140, 16, v93
	v_and_b32_e32 v141, 0xffff0000, v93
	v_pk_add_f32 v[140:141], v[140:141], v[142:143]
	v_lshlrev_b32_e32 v142, 16, v85
	v_and_b32_e32 v143, 0xffff0000, v85
	v_max_f32_e32 v85, v142, v142
	v_max_f32_e32 v85, 0xc2700000, v85
	v_mul_f32_e32 v85, 0xbfb8aa3b, v85
	v_exp_f32_e32 v85, v85
	v_and_b32_e32 v93, 0xffff0000, v88
	v_add_f32_e32 v85, 1.0, v85
	v_rcp_f32_e32 v150, v85
	v_max_f32_e32 v85, v143, v143
	v_max_f32_e32 v85, 0xc2700000, v85
	v_mul_f32_e32 v85, 0xbfb8aa3b, v85
	v_exp_f32_e32 v85, v85
	s_nop 0
	v_add_f32_e32 v85, 1.0, v85
	v_rcp_f32_e32 v151, v85
	s_nop 0
	v_pk_mul_f32 v[142:143], v[150:151], v[142:143]
	v_lshlrev_b32_e32 v150, 16, v92
	v_and_b32_e32 v151, 0xffff0000, v92
	v_lshlrev_b32_e32 v92, 16, v88
	v_pk_add_f32 v[88:89], v[150:151], v[92:93]
	v_mov_b32_e32 v151, v141
	v_mov_b32_e32 v150, v89
	v_mov_b32_e32 v92, v88
	v_mov_b32_e32 v93, v140
	v_pk_mul_f32 v[150:151], v[150:151], v[150:151]
	s_nop 0
	v_pk_fma_f32 v[92:93], v[92:93], v[92:93], v[150:151]
	v_lshlrev_b32_e32 v150, 16, v84
	v_and_b32_e32 v151, 0xffff0000, v84
	v_max_f32_e32 v84, v150, v150
	v_max_f32_e32 v85, v151, v151
	v_max_f32_e32 v84, 0xc2700000, v84
	v_max_f32_e32 v85, 0xc2700000, v85
	v_mul_f32_e32 v84, 0xbfb8aa3b, v84
	v_mul_f32_e32 v85, 0xbfb8aa3b, v85
	v_exp_f32_e32 v84, v84
	v_exp_f32_e32 v85, v85
	v_add_f32_e32 v84, 1.0, v84
	v_add_f32_e32 v85, 1.0, v85
	v_rcp_f32_e32 v84, v84
	v_rcp_f32_e32 v85, v85
	s_nop 0
	v_pk_mul_f32 v[150:151], v[84:85], v[150:151]
	v_mov_b32_e32 v84, v92
	v_mov_b32_e32 v85, v138
	v_mov_b32_e32 v138, v93
	v_pk_add_f32 v[84:85], v[84:85], v[138:139]
	v_mov_b32_e32 v92, v149
	v_mov_b32_e32 v93, v133
	v_pk_add_f32 v[84:85], v[92:93], v[84:85]
	v_mov_b32_e32 v149, v132
	v_pk_add_f32 v[84:85], v[148:149], v[84:85]
	ds_bpermute_b32 v93, v146, v85
	ds_bpermute_b32 v92, v146, v84
	s_waitcnt lgkmcnt(0)
	v_pk_add_f32 v[84:85], v[84:85], v[92:93]
	ds_bpermute_b32 v93, v145, v85
	ds_bpermute_b32 v92, v145, v84
	s_waitcnt lgkmcnt(0)
	v_pk_add_f32 v[84:85], v[84:85], v[92:93]
	ds_bpermute_b32 v93, v3, v85
	ds_bpermute_b32 v92, v3, v84
	s_waitcnt lgkmcnt(0)
	v_pk_add_f32 v[92:93], v[84:85], v[92:93]
	v_mov_b64_e32 v[84:85], s[24:25]
	v_pk_fma_f32 v[92:93], v[92:93], s[80:81], v[84:85] op_sel_hi:[1,0,0]
	s_nop 0
	v_mul_f32_e32 v86, 0x4b800000, v93
	v_cmp_gt_f32_e64 s[38:39], s79, v93
	v_cmp_gt_f32_e32 vcc, s79, v92
	s_nop 0
	v_cndmask_b32_e64 v86, v93, v86, s[38:39]
	v_rsq_f32_e32 v86, v86
	s_nop 0
	v_mul_f32_e32 v93, 0x45800000, v86
	v_cndmask_b32_e64 v86, v86, v93, s[38:39]
	v_pk_mul_f32 v[100:101], v[100:101], v[86:87] op_sel_hi:[1,0]
	v_pk_mul_f32 v[102:103], v[102:103], v[86:87] op_sel_hi:[1,0]
	v_pk_mul_f32 v[100:101], v[8:9], v[100:101]
	v_pk_mul_f32 v[102:103], v[4:5], v[102:103]
	v_pk_mul_f32 v[100:101], v[104:105], v[100:101]
	v_pk_mul_f32 v[104:105], v[130:131], v[86:87] op_sel_hi:[1,0]
	v_cvt_pk_bf16_f32 v100, v100, v101
	v_pk_mul_f32 v[104:105], v[10:11], v[104:105]
	v_pk_mul_f32 v[102:103], v[106:107], v[102:103]
	v_pk_mul_f32 v[104:105], v[136:137], v[104:105]
	v_cvt_pk_bf16_f32 v102, v102, v103
	v_cvt_pk_bf16_f32 v101, v104, v105
	v_pk_mul_f32 v[104:105], v[122:123], v[86:87] op_sel_hi:[1,0]
	v_mul_f32_e32 v86, 0x4b800000, v92
	v_cndmask_b32_e32 v86, v92, v86, vcc
	v_rsq_f32_e32 v86, v86
	v_pk_mul_f32 v[104:105], v[6:7], v[104:105]
	v_mul_f32_e32 v92, 0x45800000, v86
	v_cndmask_b32_e32 v86, v86, v92, vcc
	v_pk_mul_f32 v[88:89], v[88:89], v[86:87] op_sel_hi:[1,0]
	v_pk_mul_f32 v[92:93], v[140:141], v[86:87] op_sel_hi:[1,0]
	v_pk_mul_f32 v[88:89], v[8:9], v[88:89]
	v_pk_mul_f32 v[92:93], v[10:11], v[92:93]
	v_pk_mul_f32 v[90:91], v[90:91], v[86:87] op_sel_hi:[1,0]
	v_pk_mul_f32 v[88:89], v[150:151], v[88:89]
	v_pk_mul_f32 v[92:93], v[142:143], v[92:93]
	v_pk_mul_f32 v[90:91], v[4:5], v[90:91]
	v_cvt_pk_bf16_f32 v88, v88, v89
	v_cvt_pk_bf16_f32 v89, v92, v93
	v_pk_mul_f32 v[90:91], v[94:95], v[90:91]
	v_lshlrev_b32_e32 v92, 16, v87
	v_and_b32_e32 v93, 0xffff0000, v87
	v_cvt_pk_bf16_f32 v90, v90, v91
	v_max_f32_e32 v87, v92, v92
	v_max_f32_e32 v91, v93, v93
	v_max_f32_e32 v87, 0xc2700000, v87
	v_max_f32_e32 v91, 0xc2700000, v91
	v_mul_f32_e32 v87, 0xbfb8aa3b, v87
	v_mul_f32_e32 v91, 0xbfb8aa3b, v91
	v_exp_f32_e32 v87, v87
	v_exp_f32_e32 v91, v91
	v_pk_mul_f32 v[98:99], v[98:99], v[104:105]
	v_add_f32_e32 v87, 1.0, v87
	v_add_f32_e32 v91, 1.0, v91
	v_rcp_f32_e32 v94, v87
	v_rcp_f32_e32 v95, v91
	v_pk_mul_f32 v[86:87], v[96:97], v[86:87] op_sel_hi:[1,0]
	v_cvt_pk_bf16_f32 v103, v98, v99
	v_pk_mul_f32 v[86:87], v[6:7], v[86:87]
	v_pk_mul_f32 v[92:93], v[94:95], v[92:93]
	v_add_co_u32_e64 v98, s[38:39], s81, v134
	v_pk_mul_f32 v[86:87], v[92:93], v[86:87]
	s_waitcnt vmcnt(16)
	v_lshlrev_b32_e32 v92, 16, v81
	v_cvt_pk_bf16_f32 v91, v86, v87
	v_lshlrev_b64 v[86:87], 11, v[120:121]
	v_lshl_add_u64 v[86:87], s[46:47], 0, v[86:87]
	v_lshl_add_u64 v[86:87], v[86:87], 0, s[54:55]
	v_lshl_add_u64 v[86:87], v[86:87], 0, v[0:1]
	v_add_co_u32_e32 v86, vcc, s81, v86
	v_and_b32_e32 v93, 0xffff0000, v81
	s_nop 0
	v_addc_co_u32_e32 v87, vcc, 0, v87, vcc
	global_store_dwordx4 v[86:87], v[88:91], off offset:1024
	v_lshlrev_b32_e32 v86, 16, v79
	v_and_b32_e32 v87, 0xffff0000, v79
	v_lshlrev_b32_e32 v88, 16, v83
	v_and_b32_e32 v89, 0xffff0000, v83
	v_pk_add_f32 v[86:87], v[86:87], v[88:89]
	v_lshlrev_b32_e32 v88, 16, v78
	v_and_b32_e32 v89, 0xffff0000, v78
	v_lshlrev_b32_e32 v78, 16, v82
	v_and_b32_e32 v79, 0xffff0000, v82
	v_pk_add_f32 v[78:79], v[88:89], v[78:79]
	v_mov_b32_e32 v88, v87
	v_mov_b32_e32 v89, v79
	v_mov_b32_e32 v82, v86
	v_mov_b32_e32 v83, v78
	v_pk_mul_f32 v[88:89], v[88:89], v[88:89]
	v_addc_co_u32_e64 v99, s[38:39], 0, v135, s[38:39]
	v_pk_fma_f32 v[90:91], v[82:83], v[82:83], v[88:89]
	s_waitcnt vmcnt(16)
	v_lshlrev_b32_e32 v82, 16, v74
	v_and_b32_e32 v83, 0xffff0000, v74
	v_max_f32_e32 v74, v82, v82
	v_max_f32_e32 v74, 0xc2700000, v74
	v_mul_f32_e32 v74, 0xbfb8aa3b, v74
	v_exp_f32_e32 v74, v74
	global_store_dwordx4 v[98:99], v[100:103], off offset:1024
	s_waitcnt vmcnt(15)
	v_lshlrev_b32_e32 v98, 16, v67
	v_and_b32_e32 v99, 0xffff0000, v67
	v_add_f32_e32 v74, 1.0, v74
	v_rcp_f32_e32 v88, v74
	v_max_f32_e32 v74, v83, v83
	v_max_f32_e32 v74, 0xc2700000, v74
	v_mul_f32_e32 v74, 0xbfb8aa3b, v74
	v_exp_f32_e32 v74, v74
	v_lshlrev_b32_e32 v100, 16, v65
	v_and_b32_e32 v101, 0xffff0000, v65
	v_add_f32_e32 v74, 1.0, v74
	v_rcp_f32_e32 v89, v74
	s_nop 0
	v_pk_mul_f32 v[82:83], v[88:89], v[82:83]
	v_lshlrev_b32_e32 v88, 16, v77
	v_and_b32_e32 v89, 0xffff0000, v77
	v_pk_add_f32 v[88:89], v[88:89], v[92:93]
	v_lshlrev_b32_e32 v92, 16, v73
	v_and_b32_e32 v93, 0xffff0000, v73
	v_max_f32_e32 v73, v92, v92
	v_max_f32_e32 v73, 0xc2700000, v73
	v_mul_f32_e32 v73, 0xbfb8aa3b, v73
	v_exp_f32_e32 v73, v73
	v_and_b32_e32 v77, 0xffff0000, v80
	v_mov_b32_e32 v81, v88
	v_add_f32_e32 v73, 1.0, v73
	v_rcp_f32_e32 v94, v73
	v_max_f32_e32 v73, v93, v93
	v_max_f32_e32 v73, 0xc2700000, v73
	v_mul_f32_e32 v73, 0xbfb8aa3b, v73
	v_exp_f32_e32 v73, v73
	s_nop 0
	v_add_f32_e32 v73, 1.0, v73
	v_rcp_f32_e32 v95, v73
	s_nop 0
	v_pk_mul_f32 v[92:93], v[94:95], v[92:93]
	v_lshlrev_b32_e32 v94, 16, v76
	v_and_b32_e32 v95, 0xffff0000, v76
	v_lshlrev_b32_e32 v76, 16, v80
	v_pk_add_f32 v[76:77], v[94:95], v[76:77]
	v_mov_b32_e32 v95, v89
	v_mov_b32_e32 v94, v77
	v_mov_b32_e32 v80, v76
	v_pk_mul_f32 v[94:95], v[94:95], v[94:95]
	s_nop 0
	v_pk_fma_f32 v[96:97], v[80:81], v[80:81], v[94:95]
	v_lshlrev_b32_e32 v80, 16, v72
	v_and_b32_e32 v81, 0xffff0000, v72
	v_max_f32_e32 v72, v80, v80
	v_max_f32_e32 v73, v81, v81
	v_max_f32_e32 v72, 0xc2700000, v72
	v_max_f32_e32 v73, 0xc2700000, v73
	v_mul_f32_e32 v72, 0xbfb8aa3b, v72
	v_mul_f32_e32 v73, 0xbfb8aa3b, v73
	v_exp_f32_e32 v72, v72
	v_exp_f32_e32 v73, v73
	v_add_f32_e32 v72, 1.0, v72
	v_add_f32_e32 v73, 1.0, v73
	v_rcp_f32_e32 v72, v72
	v_rcp_f32_e32 v73, v73
	s_nop 0
	v_pk_mul_f32 v[80:81], v[72:73], v[80:81]
	v_lshlrev_b32_e32 v72, 16, v75
	v_and_b32_e32 v73, 0xffff0000, v75
	v_max_f32_e32 v74, v72, v72
	v_max_f32_e32 v75, v73, v73
	v_max_f32_e32 v74, 0xc2700000, v74
	v_max_f32_e32 v75, 0xc2700000, v75
	v_mul_f32_e32 v74, 0xbfb8aa3b, v74
	v_mul_f32_e32 v75, 0xbfb8aa3b, v75
	v_exp_f32_e32 v74, v74
	v_exp_f32_e32 v75, v75
	v_add_f32_e32 v74, 1.0, v74
	v_add_f32_e32 v75, 1.0, v75
	v_rcp_f32_e32 v74, v74
	v_rcp_f32_e32 v75, v75
	s_nop 0
	v_pk_mul_f32 v[74:75], v[74:75], v[72:73]
	v_lshlrev_b64 v[72:73], 11, v[118:119]
	v_lshl_add_u64 v[72:73], s[46:47], 0, v[72:73]
	v_lshl_add_u64 v[72:73], v[72:73], 0, s[54:55]
	v_lshl_add_u64 v[94:95], v[72:73], 0, v[0:1]
	v_lshlrev_b32_e32 v72, 16, v71
	v_and_b32_e32 v73, 0xffff0000, v71
	v_pk_add_f32 v[72:73], v[72:73], v[98:99]
	v_lshlrev_b32_e32 v98, 16, v70
	v_and_b32_e32 v99, 0xffff0000, v70
	v_lshlrev_b32_e32 v70, 16, v66
	v_and_b32_e32 v71, 0xffff0000, v66
	v_pk_add_f32 v[66:67], v[98:99], v[70:71]
	v_mov_b32_e32 v98, v73
	v_mov_b32_e32 v99, v67
	v_mov_b32_e32 v70, v72
	v_mov_b32_e32 v71, v66
	v_pk_mul_f32 v[98:99], v[98:99], v[98:99]
	s_nop 0
	v_pk_fma_f32 v[102:103], v[70:71], v[70:71], v[98:99]
	s_waitcnt vmcnt(14)
	v_lshlrev_b32_e32 v70, 16, v62
	v_and_b32_e32 v71, 0xffff0000, v62
	v_max_f32_e32 v62, v70, v70
	v_max_f32_e32 v62, 0xc2700000, v62
	v_mul_f32_e32 v62, 0xbfb8aa3b, v62
	v_exp_f32_e32 v62, v62
	s_nop 0
	v_add_f32_e32 v62, 1.0, v62
	v_rcp_f32_e32 v98, v62
	v_max_f32_e32 v62, v71, v71
	v_max_f32_e32 v62, 0xc2700000, v62
	v_mul_f32_e32 v62, 0xbfb8aa3b, v62
	v_exp_f32_e32 v62, v62
	s_nop 0
	v_add_f32_e32 v62, 1.0, v62
	v_rcp_f32_e32 v99, v62
	s_nop 0
	v_pk_mul_f32 v[70:71], v[98:99], v[70:71]
	v_lshlrev_b32_e32 v98, 16, v69
	v_and_b32_e32 v99, 0xffff0000, v69
	v_pk_add_f32 v[98:99], v[98:99], v[100:101]
	v_lshlrev_b32_e32 v100, 16, v61
	v_and_b32_e32 v101, 0xffff0000, v61
	v_max_f32_e32 v61, v100, v100
	v_max_f32_e32 v61, 0xc2700000, v61
	v_mul_f32_e32 v61, 0xbfb8aa3b, v61
	v_exp_f32_e32 v61, v61
	v_and_b32_e32 v69, 0xffff0000, v64
	v_add_f32_e32 v61, 1.0, v61
	v_rcp_f32_e32 v104, v61
	v_max_f32_e32 v61, v101, v101
	v_max_f32_e32 v61, 0xc2700000, v61
	v_mul_f32_e32 v61, 0xbfb8aa3b, v61
	v_exp_f32_e32 v61, v61
	s_nop 0
	v_add_f32_e32 v61, 1.0, v61
	v_rcp_f32_e32 v105, v61
	s_nop 0
	v_pk_mul_f32 v[100:101], v[104:105], v[100:101]
	v_lshlrev_b32_e32 v104, 16, v68
	v_and_b32_e32 v105, 0xffff0000, v68
	v_lshlrev_b32_e32 v68, 16, v64
	v_pk_add_f32 v[64:65], v[104:105], v[68:69]
	v_mov_b32_e32 v105, v99
	v_mov_b32_e32 v104, v65
	v_mov_b32_e32 v68, v64
	v_mov_b32_e32 v69, v98
	v_pk_mul_f32 v[104:105], v[104:105], v[104:105]
	s_nop 0
	v_pk_fma_f32 v[68:69], v[68:69], v[68:69], v[104:105]
	v_lshlrev_b32_e32 v104, 16, v60
	v_and_b32_e32 v105, 0xffff0000, v60
	v_max_f32_e32 v60, v104, v104
	v_max_f32_e32 v61, v105, v105
	v_max_f32_e32 v60, 0xc2700000, v60
	v_max_f32_e32 v61, 0xc2700000, v61
	v_mul_f32_e32 v60, 0xbfb8aa3b, v60
	v_mul_f32_e32 v61, 0xbfb8aa3b, v61
	v_exp_f32_e32 v60, v60
	v_exp_f32_e32 v61, v61
	v_add_f32_e32 v60, 1.0, v60
	v_add_f32_e32 v61, 1.0, v61
	v_rcp_f32_e32 v60, v60
	v_rcp_f32_e32 v61, v61
	s_nop 0
	v_pk_mul_f32 v[60:61], v[60:61], v[104:105]
	v_mov_b32_e32 v104, v68
	v_mov_b32_e32 v105, v96
	v_mov_b32_e32 v96, v69
	v_pk_add_f32 v[68:69], v[104:105], v[96:97]
	v_mov_b32_e32 v96, v103
	v_mov_b32_e32 v97, v91
	v_pk_add_f32 v[68:69], v[96:97], v[68:69]
	v_mov_b32_e32 v103, v90
	v_pk_add_f32 v[68:69], v[102:103], v[68:69]
	ds_bpermute_b32 v91, v146, v69
	ds_bpermute_b32 v90, v146, v68
	s_waitcnt lgkmcnt(0)
	v_pk_add_f32 v[68:69], v[68:69], v[90:91]
	ds_bpermute_b32 v91, v145, v69
	ds_bpermute_b32 v90, v145, v68
	s_waitcnt lgkmcnt(0)
	v_pk_add_f32 v[68:69], v[68:69], v[90:91]
	ds_bpermute_b32 v91, v3, v69
	ds_bpermute_b32 v90, v3, v68
	s_waitcnt lgkmcnt(0)
	v_pk_add_f32 v[68:69], v[68:69], v[90:91]
	s_nop 0
	v_pk_fma_f32 v[68:69], v[68:69], s[80:81], v[84:85] op_sel_hi:[1,0,0]
	s_nop 0
	v_mul_f32_e32 v62, 0x4b800000, v69
	v_cmp_gt_f32_e64 s[38:39], s79, v69
	v_cmp_gt_f32_e32 vcc, s79, v68
	s_nop 0
	v_cndmask_b32_e64 v62, v69, v62, s[38:39]
	v_rsq_f32_e32 v62, v62
	s_nop 0
	v_mul_f32_e32 v69, 0x45800000, v62
	v_cndmask_b32_e64 v62, v62, v69, s[38:39]
	v_pk_mul_f32 v[76:77], v[76:77], v[62:63] op_sel_hi:[1,0]
	v_pk_mul_f32 v[78:79], v[78:79], v[62:63] op_sel_hi:[1,0]
	v_pk_mul_f32 v[76:77], v[8:9], v[76:77]
	v_pk_mul_f32 v[78:79], v[4:5], v[78:79]
	v_pk_mul_f32 v[76:77], v[80:81], v[76:77]
	v_pk_mul_f32 v[80:81], v[88:89], v[62:63] op_sel_hi:[1,0]
	v_cvt_pk_bf16_f32 v76, v76, v77
	v_pk_mul_f32 v[80:81], v[10:11], v[80:81]
	v_pk_mul_f32 v[78:79], v[82:83], v[78:79]
	v_pk_mul_f32 v[80:81], v[92:93], v[80:81]
	v_cvt_pk_bf16_f32 v78, v78, v79
	v_cvt_pk_bf16_f32 v77, v80, v81
	v_pk_mul_f32 v[80:81], v[86:87], v[62:63] op_sel_hi:[1,0]
	v_mul_f32_e32 v62, 0x4b800000, v68
	v_cndmask_b32_e32 v62, v68, v62, vcc
	v_rsq_f32_e32 v62, v62
	v_pk_mul_f32 v[80:81], v[6:7], v[80:81]
	v_mul_f32_e32 v68, 0x45800000, v62
	v_cndmask_b32_e32 v68, v62, v68, vcc
	v_pk_mul_f32 v[64:65], v[64:65], v[68:69] op_sel_hi:[1,0]
	v_pk_mul_f32 v[74:75], v[74:75], v[80:81]
	v_pk_mul_f32 v[64:65], v[8:9], v[64:65]
	v_cvt_pk_bf16_f32 v79, v74, v75
	v_pk_mul_f32 v[60:61], v[60:61], v[64:65]
	v_pk_mul_f32 v[64:65], v[98:99], v[68:69] op_sel_hi:[1,0]
	v_cvt_pk_bf16_f32 v60, v60, v61
	v_pk_mul_f32 v[64:65], v[10:11], v[64:65]
	v_add_co_u32_e64 v74, s[38:39], s81, v94
	v_pk_mul_f32 v[64:65], v[100:101], v[64:65]
	s_nop 0
	v_addc_co_u32_e64 v75, s[38:39], 0, v95, s[38:39]
	v_cvt_pk_bf16_f32 v61, v64, v65
	v_pk_mul_f32 v[64:65], v[66:67], v[68:69] op_sel_hi:[1,0]
	v_pk_mul_f32 v[68:69], v[72:73], v[68:69] op_sel_hi:[1,0]
	v_pk_mul_f32 v[64:65], v[4:5], v[64:65]
	v_pk_mul_f32 v[68:69], v[6:7], v[68:69]
	v_pk_mul_f32 v[64:65], v[70:71], v[64:65]
	s_waitcnt vmcnt(9)
	v_lshlrev_b32_e32 v72, 16, v43
	v_cvt_pk_bf16_f32 v62, v64, v65
	v_lshlrev_b32_e32 v64, 16, v63
	v_and_b32_e32 v65, 0xffff0000, v63
	v_max_f32_e32 v63, v64, v64
	v_max_f32_e32 v63, 0xc2700000, v63
	v_mul_f32_e32 v63, 0xbfb8aa3b, v63
	v_exp_f32_e32 v63, v63
	v_and_b32_e32 v73, 0xffff0000, v43
	global_store_dwordx4 v[74:75], v[76:79], off offset:1024
	v_lshlrev_b32_e32 v74, 16, v41
	v_add_f32_e32 v63, 1.0, v63
	v_rcp_f32_e32 v66, v63
	v_max_f32_e32 v63, v65, v65
	v_max_f32_e32 v63, 0xc2700000, v63
	v_mul_f32_e32 v63, 0xbfb8aa3b, v63
	v_exp_f32_e32 v63, v63
	v_and_b32_e32 v75, 0xffff0000, v41
	v_add_f32_e32 v63, 1.0, v63
	v_rcp_f32_e32 v67, v63
	s_nop 0
	v_pk_mul_f32 v[64:65], v[66:67], v[64:65]
	s_nop 0
	v_pk_mul_f32 v[64:65], v[64:65], v[68:69]
	v_lshlrev_b32_e32 v66, 16, v57
	v_cvt_pk_bf16_f32 v63, v64, v65
	v_lshlrev_b64 v[64:65], 11, v[116:117]
	v_lshl_add_u64 v[64:65], s[46:47], 0, v[64:65]
	v_lshl_add_u64 v[64:65], v[64:65], 0, s[54:55]
	v_lshl_add_u64 v[64:65], v[64:65], 0, v[0:1]
	v_add_co_u32_e32 v64, vcc, s81, v64
	v_and_b32_e32 v67, 0xffff0000, v57
	s_nop 0
	v_addc_co_u32_e32 v65, vcc, 0, v65, vcc
	global_store_dwordx4 v[64:65], v[60:63], off offset:1024
	s_nop 1
	v_lshlrev_b32_e32 v60, 16, v55
	v_and_b32_e32 v61, 0xffff0000, v55
	v_lshlrev_b32_e32 v62, 16, v59
	v_and_b32_e32 v63, 0xffff0000, v59
	v_pk_add_f32 v[60:61], v[60:61], v[62:63]
	v_lshlrev_b32_e32 v62, 16, v54
	v_and_b32_e32 v63, 0xffff0000, v54
	v_lshlrev_b32_e32 v54, 16, v58
	v_and_b32_e32 v55, 0xffff0000, v58
	v_pk_add_f32 v[54:55], v[62:63], v[54:55]
	v_mov_b32_e32 v62, v61
	v_mov_b32_e32 v63, v55
	v_mov_b32_e32 v58, v60
	v_mov_b32_e32 v59, v54
	v_pk_mul_f32 v[62:63], v[62:63], v[62:63]
	s_nop 0
	v_pk_fma_f32 v[64:65], v[58:59], v[58:59], v[62:63]
	v_lshlrev_b32_e32 v58, 16, v50
	v_and_b32_e32 v59, 0xffff0000, v50
	v_max_f32_e32 v50, v58, v58
	v_max_f32_e32 v50, 0xc2700000, v50
	v_mul_f32_e32 v50, 0xbfb8aa3b, v50
	v_exp_f32_e32 v50, v50
	s_nop 0
	v_add_f32_e32 v50, 1.0, v50
	v_rcp_f32_e32 v62, v50
	v_max_f32_e32 v50, v59, v59
	v_max_f32_e32 v50, 0xc2700000, v50
	v_mul_f32_e32 v50, 0xbfb8aa3b, v50
	v_exp_f32_e32 v50, v50
	s_nop 0
	v_add_f32_e32 v50, 1.0, v50
	v_rcp_f32_e32 v63, v50
	s_nop 0
	v_pk_mul_f32 v[58:59], v[62:63], v[58:59]
	v_lshlrev_b32_e32 v62, 16, v53
	v_and_b32_e32 v63, 0xffff0000, v53
	v_pk_add_f32 v[62:63], v[62:63], v[66:67]
	v_lshlrev_b32_e32 v66, 16, v49
	v_and_b32_e32 v67, 0xffff0000, v49
	v_max_f32_e32 v49, v66, v66
	v_max_f32_e32 v49, 0xc2700000, v49
	v_mul_f32_e32 v49, 0xbfb8aa3b, v49
	v_exp_f32_e32 v49, v49
	v_and_b32_e32 v53, 0xffff0000, v56
	v_mov_b32_e32 v57, v62
	v_add_f32_e32 v49, 1.0, v49
	v_rcp_f32_e32 v68, v49
	v_max_f32_e32 v49, v67, v67
	v_max_f32_e32 v49, 0xc2700000, v49
	v_mul_f32_e32 v49, 0xbfb8aa3b, v49
	v_exp_f32_e32 v49, v49
	s_nop 0
	v_add_f32_e32 v49, 1.0, v49
	v_rcp_f32_e32 v69, v49
	s_nop 0
	v_pk_mul_f32 v[66:67], v[68:69], v[66:67]
	v_lshlrev_b32_e32 v68, 16, v52
	v_and_b32_e32 v69, 0xffff0000, v52
	v_lshlrev_b32_e32 v52, 16, v56
	v_pk_add_f32 v[52:53], v[68:69], v[52:53]
	v_mov_b32_e32 v69, v63
	v_mov_b32_e32 v68, v53
	v_mov_b32_e32 v56, v52
	v_pk_mul_f32 v[68:69], v[68:69], v[68:69]
	s_nop 0
	v_pk_fma_f32 v[70:71], v[56:57], v[56:57], v[68:69]
	v_lshlrev_b32_e32 v56, 16, v48
	v_and_b32_e32 v57, 0xffff0000, v48
	v_max_f32_e32 v48, v56, v56
	v_max_f32_e32 v49, v57, v57
	v_max_f32_e32 v48, 0xc2700000, v48
	v_max_f32_e32 v49, 0xc2700000, v49
	v_mul_f32_e32 v48, 0xbfb8aa3b, v48
	v_mul_f32_e32 v49, 0xbfb8aa3b, v49
	v_exp_f32_e32 v48, v48
	v_exp_f32_e32 v49, v49
	v_add_f32_e32 v48, 1.0, v48
	v_add_f32_e32 v49, 1.0, v49
	v_rcp_f32_e32 v48, v48
	v_rcp_f32_e32 v49, v49
	s_nop 0
	v_pk_mul_f32 v[56:57], v[48:49], v[56:57]
	v_lshlrev_b32_e32 v48, 16, v51
	v_and_b32_e32 v49, 0xffff0000, v51
	v_max_f32_e32 v50, v48, v48
	v_max_f32_e32 v51, v49, v49
	v_max_f32_e32 v50, 0xc2700000, v50
	v_max_f32_e32 v51, 0xc2700000, v51
	v_mul_f32_e32 v50, 0xbfb8aa3b, v50
	v_mul_f32_e32 v51, 0xbfb8aa3b, v51
	v_exp_f32_e32 v50, v50
	v_exp_f32_e32 v51, v51
	v_add_f32_e32 v50, 1.0, v50
	v_add_f32_e32 v51, 1.0, v51
	v_rcp_f32_e32 v50, v50
	v_rcp_f32_e32 v51, v51
	s_nop 0
	v_pk_mul_f32 v[50:51], v[50:51], v[48:49]
	v_lshlrev_b64 v[48:49], 11, v[114:115]
	v_lshl_add_u64 v[48:49], s[46:47], 0, v[48:49]
	v_lshl_add_u64 v[48:49], v[48:49], 0, s[54:55]
	v_lshl_add_u64 v[68:69], v[48:49], 0, v[0:1]
	v_lshlrev_b32_e32 v48, 16, v47
	v_and_b32_e32 v49, 0xffff0000, v47
	v_pk_add_f32 v[48:49], v[48:49], v[72:73]
	v_lshlrev_b32_e32 v72, 16, v46
	v_and_b32_e32 v73, 0xffff0000, v46
	v_lshlrev_b32_e32 v46, 16, v42
	v_and_b32_e32 v47, 0xffff0000, v42
	v_pk_add_f32 v[42:43], v[72:73], v[46:47]
	v_mov_b32_e32 v72, v49
	v_mov_b32_e32 v73, v43
	v_mov_b32_e32 v46, v48
	v_mov_b32_e32 v47, v42
	v_pk_mul_f32 v[72:73], v[72:73], v[72:73]
	s_nop 0
	v_pk_fma_f32 v[76:77], v[46:47], v[46:47], v[72:73]
	s_waitcnt vmcnt(10)
	v_lshlrev_b32_e32 v46, 16, v38
	v_and_b32_e32 v47, 0xffff0000, v38
	v_max_f32_e32 v38, v46, v46
	v_max_f32_e32 v38, 0xc2700000, v38
	v_mul_f32_e32 v38, 0xbfb8aa3b, v38
	v_exp_f32_e32 v38, v38
	s_nop 0
	v_add_f32_e32 v38, 1.0, v38
	v_rcp_f32_e32 v72, v38
	v_max_f32_e32 v38, v47, v47
	v_max_f32_e32 v38, 0xc2700000, v38
	v_mul_f32_e32 v38, 0xbfb8aa3b, v38
	v_exp_f32_e32 v38, v38
	s_nop 0
	v_add_f32_e32 v38, 1.0, v38
	v_rcp_f32_e32 v73, v38
	s_nop 0
	v_pk_mul_f32 v[46:47], v[72:73], v[46:47]
	v_lshlrev_b32_e32 v72, 16, v45
	v_and_b32_e32 v73, 0xffff0000, v45
	v_pk_add_f32 v[72:73], v[72:73], v[74:75]
	v_lshlrev_b32_e32 v74, 16, v37
	v_and_b32_e32 v75, 0xffff0000, v37
	v_max_f32_e32 v37, v74, v74
	v_max_f32_e32 v37, 0xc2700000, v37
	v_mul_f32_e32 v37, 0xbfb8aa3b, v37
	v_exp_f32_e32 v37, v37
	v_and_b32_e32 v45, 0xffff0000, v40
	v_add_f32_e32 v37, 1.0, v37
	v_rcp_f32_e32 v78, v37
	v_max_f32_e32 v37, v75, v75
	v_max_f32_e32 v37, 0xc2700000, v37
	v_mul_f32_e32 v37, 0xbfb8aa3b, v37
	v_exp_f32_e32 v37, v37
	s_nop 0
	v_add_f32_e32 v37, 1.0, v37
	v_rcp_f32_e32 v79, v37
	s_nop 0
	v_pk_mul_f32 v[74:75], v[78:79], v[74:75]
	v_lshlrev_b32_e32 v78, 16, v44
	v_and_b32_e32 v79, 0xffff0000, v44
	v_lshlrev_b32_e32 v44, 16, v40
	v_pk_add_f32 v[40:41], v[78:79], v[44:45]
	v_mov_b32_e32 v79, v73
	v_mov_b32_e32 v78, v41
	v_mov_b32_e32 v44, v40
	v_mov_b32_e32 v45, v72
	v_pk_mul_f32 v[78:79], v[78:79], v[78:79]
	s_nop 0
	v_pk_fma_f32 v[44:45], v[44:45], v[44:45], v[78:79]
	v_lshlrev_b32_e32 v78, 16, v36
	v_and_b32_e32 v79, 0xffff0000, v36
	v_max_f32_e32 v36, v78, v78
	v_max_f32_e32 v37, v79, v79
	v_max_f32_e32 v36, 0xc2700000, v36
	v_max_f32_e32 v37, 0xc2700000, v37
	v_mul_f32_e32 v36, 0xbfb8aa3b, v36
	v_mul_f32_e32 v37, 0xbfb8aa3b, v37
	v_exp_f32_e32 v36, v36
	v_exp_f32_e32 v37, v37
	v_add_f32_e32 v36, 1.0, v36
	v_add_f32_e32 v37, 1.0, v37
	v_rcp_f32_e32 v36, v36
	v_rcp_f32_e32 v37, v37
	s_nop 0
	v_pk_mul_f32 v[36:37], v[36:37], v[78:79]
	v_mov_b32_e32 v78, v44
	v_mov_b32_e32 v79, v70
	v_mov_b32_e32 v70, v45
	v_pk_add_f32 v[44:45], v[78:79], v[70:71]
	v_mov_b32_e32 v70, v77
	v_mov_b32_e32 v71, v65
	v_pk_add_f32 v[44:45], v[70:71], v[44:45]
	v_mov_b32_e32 v77, v64
	v_pk_add_f32 v[44:45], v[76:77], v[44:45]
	ds_bpermute_b32 v65, v146, v45
	ds_bpermute_b32 v64, v146, v44
	s_waitcnt lgkmcnt(0)
	v_pk_add_f32 v[44:45], v[44:45], v[64:65]
	ds_bpermute_b32 v65, v145, v45
	ds_bpermute_b32 v64, v145, v44
	s_waitcnt lgkmcnt(0)
	v_pk_add_f32 v[44:45], v[44:45], v[64:65]
	ds_bpermute_b32 v65, v3, v45
	ds_bpermute_b32 v64, v3, v44
	s_waitcnt lgkmcnt(0)
	v_pk_add_f32 v[44:45], v[44:45], v[64:65]
	s_nop 0
	v_pk_fma_f32 v[44:45], v[44:45], s[80:81], v[84:85] op_sel_hi:[1,0,0]
	s_nop 0
	v_mul_f32_e32 v38, 0x4b800000, v45
	v_cmp_gt_f32_e64 s[38:39], s79, v45
	v_cmp_gt_f32_e32 vcc, s79, v44
	s_nop 0
	v_cndmask_b32_e64 v38, v45, v38, s[38:39]
	v_rsq_f32_e32 v38, v38
	s_nop 0
	v_mul_f32_e32 v45, 0x45800000, v38
	v_cndmask_b32_e64 v38, v38, v45, s[38:39]
	v_pk_mul_f32 v[52:53], v[52:53], v[38:39] op_sel_hi:[1,0]
	v_pk_mul_f32 v[54:55], v[54:55], v[38:39] op_sel_hi:[1,0]
	v_pk_mul_f32 v[52:53], v[8:9], v[52:53]
	v_pk_mul_f32 v[54:55], v[4:5], v[54:55]
	v_pk_mul_f32 v[52:53], v[56:57], v[52:53]
	v_pk_mul_f32 v[56:57], v[62:63], v[38:39] op_sel_hi:[1,0]
	v_cvt_pk_bf16_f32 v52, v52, v53
	v_pk_mul_f32 v[56:57], v[10:11], v[56:57]
	v_pk_mul_f32 v[54:55], v[58:59], v[54:55]
	v_pk_mul_f32 v[56:57], v[66:67], v[56:57]
	v_cvt_pk_bf16_f32 v54, v54, v55
	v_cvt_pk_bf16_f32 v53, v56, v57
	v_pk_mul_f32 v[56:57], v[60:61], v[38:39] op_sel_hi:[1,0]
	v_mul_f32_e32 v38, 0x4b800000, v44
	v_cndmask_b32_e32 v38, v44, v38, vcc
	v_rsq_f32_e32 v38, v38
	v_pk_mul_f32 v[56:57], v[6:7], v[56:57]
	v_mul_f32_e32 v44, 0x45800000, v38
	v_cndmask_b32_e32 v44, v38, v44, vcc
	v_pk_mul_f32 v[40:41], v[40:41], v[44:45] op_sel_hi:[1,0]
	v_pk_mul_f32 v[50:51], v[50:51], v[56:57]
	v_pk_mul_f32 v[40:41], v[8:9], v[40:41]
	v_cvt_pk_bf16_f32 v55, v50, v51
	v_pk_mul_f32 v[36:37], v[36:37], v[40:41]
	v_pk_mul_f32 v[40:41], v[72:73], v[44:45] op_sel_hi:[1,0]
	v_cvt_pk_bf16_f32 v36, v36, v37
	v_pk_mul_f32 v[40:41], v[10:11], v[40:41]
	v_add_co_u32_e64 v50, s[38:39], s81, v68
	v_pk_mul_f32 v[40:41], v[74:75], v[40:41]
	s_nop 0
	v_addc_co_u32_e64 v51, s[38:39], 0, v69, s[38:39]
	v_cvt_pk_bf16_f32 v37, v40, v41
	v_pk_mul_f32 v[40:41], v[42:43], v[44:45] op_sel_hi:[1,0]
	v_pk_mul_f32 v[44:45], v[48:49], v[44:45] op_sel_hi:[1,0]
	v_pk_mul_f32 v[40:41], v[4:5], v[40:41]
	v_pk_mul_f32 v[44:45], v[6:7], v[44:45]
	v_pk_mul_f32 v[40:41], v[46:47], v[40:41]
	s_waitcnt vmcnt(5)
	v_lshlrev_b32_e32 v48, 16, v23
	v_cvt_pk_bf16_f32 v38, v40, v41
	v_lshlrev_b32_e32 v40, 16, v39
	v_and_b32_e32 v41, 0xffff0000, v39
	v_max_f32_e32 v39, v40, v40
	v_max_f32_e32 v39, 0xc2700000, v39
	v_mul_f32_e32 v39, 0xbfb8aa3b, v39
	v_exp_f32_e32 v39, v39
	v_and_b32_e32 v49, 0xffff0000, v23
	global_store_dwordx4 v[50:51], v[52:55], off offset:1024
	v_lshlrev_b32_e32 v50, 16, v21
	v_add_f32_e32 v39, 1.0, v39
	v_rcp_f32_e32 v42, v39
	v_max_f32_e32 v39, v41, v41
	v_max_f32_e32 v39, 0xc2700000, v39
	v_mul_f32_e32 v39, 0xbfb8aa3b, v39
	v_exp_f32_e32 v39, v39
	v_and_b32_e32 v51, 0xffff0000, v21
	v_add_f32_e32 v39, 1.0, v39
	v_rcp_f32_e32 v43, v39
	s_nop 0
	v_pk_mul_f32 v[40:41], v[42:43], v[40:41]
	s_nop 0
	v_pk_mul_f32 v[40:41], v[40:41], v[44:45]
	v_lshlrev_b32_e32 v42, 16, v33
	v_cvt_pk_bf16_f32 v39, v40, v41
	v_lshlrev_b64 v[40:41], 11, v[112:113]
	v_lshl_add_u64 v[40:41], s[46:47], 0, v[40:41]
	v_lshl_add_u64 v[40:41], v[40:41], 0, s[54:55]
	v_lshl_add_u64 v[40:41], v[40:41], 0, v[0:1]
	v_add_co_u32_e32 v40, vcc, s81, v40
	v_and_b32_e32 v43, 0xffff0000, v33
	s_nop 0
	v_addc_co_u32_e32 v41, vcc, 0, v41, vcc
	global_store_dwordx4 v[40:41], v[36:39], off offset:1024
	s_nop 1
	v_lshlrev_b32_e32 v36, 16, v31
	v_and_b32_e32 v37, 0xffff0000, v31
	v_lshlrev_b32_e32 v38, 16, v35
	v_and_b32_e32 v39, 0xffff0000, v35
	v_pk_add_f32 v[36:37], v[36:37], v[38:39]
	v_lshlrev_b32_e32 v38, 16, v30
	v_and_b32_e32 v39, 0xffff0000, v30
	v_lshlrev_b32_e32 v30, 16, v34
	v_and_b32_e32 v31, 0xffff0000, v34
	v_pk_add_f32 v[30:31], v[38:39], v[30:31]
	v_mov_b32_e32 v38, v37
	v_mov_b32_e32 v39, v31
	v_mov_b32_e32 v34, v36
	v_mov_b32_e32 v35, v30
	v_pk_mul_f32 v[38:39], v[38:39], v[38:39]
	s_nop 0
	v_pk_fma_f32 v[40:41], v[34:35], v[34:35], v[38:39]
	v_lshlrev_b32_e32 v34, 16, v26
	v_and_b32_e32 v35, 0xffff0000, v26
	v_max_f32_e32 v26, v34, v34
	v_max_f32_e32 v26, 0xc2700000, v26
	v_mul_f32_e32 v26, 0xbfb8aa3b, v26
	v_exp_f32_e32 v26, v26
	s_nop 0
	v_add_f32_e32 v26, 1.0, v26
	v_rcp_f32_e32 v38, v26
	v_max_f32_e32 v26, v35, v35
	v_max_f32_e32 v26, 0xc2700000, v26
	v_mul_f32_e32 v26, 0xbfb8aa3b, v26
	v_exp_f32_e32 v26, v26
	s_nop 0
	v_add_f32_e32 v26, 1.0, v26
	v_rcp_f32_e32 v39, v26
	s_nop 0
	v_pk_mul_f32 v[34:35], v[38:39], v[34:35]
	v_lshlrev_b32_e32 v38, 16, v29
	v_and_b32_e32 v39, 0xffff0000, v29
	v_pk_add_f32 v[38:39], v[38:39], v[42:43]
	v_lshlrev_b32_e32 v42, 16, v25
	v_and_b32_e32 v43, 0xffff0000, v25
	v_max_f32_e32 v25, v42, v42
	v_max_f32_e32 v25, 0xc2700000, v25
	v_mul_f32_e32 v25, 0xbfb8aa3b, v25
	v_exp_f32_e32 v25, v25
	v_and_b32_e32 v29, 0xffff0000, v32
	v_mov_b32_e32 v33, v38
	v_add_f32_e32 v25, 1.0, v25
	v_rcp_f32_e32 v44, v25
	v_max_f32_e32 v25, v43, v43
	v_max_f32_e32 v25, 0xc2700000, v25
	v_mul_f32_e32 v25, 0xbfb8aa3b, v25
	v_exp_f32_e32 v25, v25
	s_nop 0
	v_add_f32_e32 v25, 1.0, v25
	v_rcp_f32_e32 v45, v25
	s_nop 0
	v_pk_mul_f32 v[42:43], v[44:45], v[42:43]
	v_lshlrev_b32_e32 v44, 16, v28
	v_and_b32_e32 v45, 0xffff0000, v28
	v_lshlrev_b32_e32 v28, 16, v32
	v_pk_add_f32 v[28:29], v[44:45], v[28:29]
	v_mov_b32_e32 v45, v39
	v_mov_b32_e32 v44, v29
	v_mov_b32_e32 v32, v28
	v_pk_mul_f32 v[44:45], v[44:45], v[44:45]
	s_nop 0
	v_pk_fma_f32 v[46:47], v[32:33], v[32:33], v[44:45]
	v_lshlrev_b32_e32 v32, 16, v24
	v_and_b32_e32 v33, 0xffff0000, v24
	v_max_f32_e32 v24, v32, v32
	v_max_f32_e32 v25, v33, v33
	v_max_f32_e32 v24, 0xc2700000, v24
	v_max_f32_e32 v25, 0xc2700000, v25
	v_mul_f32_e32 v24, 0xbfb8aa3b, v24
	v_mul_f32_e32 v25, 0xbfb8aa3b, v25
	v_exp_f32_e32 v24, v24
	v_exp_f32_e32 v25, v25
	v_add_f32_e32 v24, 1.0, v24
	v_add_f32_e32 v25, 1.0, v25
	v_rcp_f32_e32 v24, v24
	v_rcp_f32_e32 v25, v25
	s_nop 0
	v_pk_mul_f32 v[32:33], v[24:25], v[32:33]
	v_lshlrev_b32_e32 v24, 16, v27
	v_and_b32_e32 v25, 0xffff0000, v27
	v_max_f32_e32 v26, v24, v24
	v_max_f32_e32 v27, v25, v25
	v_max_f32_e32 v26, 0xc2700000, v26
	v_max_f32_e32 v27, 0xc2700000, v27
	v_mul_f32_e32 v26, 0xbfb8aa3b, v26
	v_mul_f32_e32 v27, 0xbfb8aa3b, v27
	v_exp_f32_e32 v26, v26
	v_exp_f32_e32 v27, v27
	v_add_f32_e32 v26, 1.0, v26
	v_add_f32_e32 v27, 1.0, v27
	v_rcp_f32_e32 v26, v26
	v_rcp_f32_e32 v27, v27
	s_nop 0
	v_pk_mul_f32 v[26:27], v[26:27], v[24:25]
	v_lshlrev_b64 v[24:25], 11, v[110:111]
	v_lshl_add_u64 v[24:25], s[46:47], 0, v[24:25]
	v_lshl_add_u64 v[24:25], v[24:25], 0, s[54:55]
	v_lshl_add_u64 v[44:45], v[24:25], 0, v[0:1]
	v_lshlrev_b32_e32 v24, 16, v19
	v_and_b32_e32 v25, 0xffff0000, v19
	v_pk_add_f32 v[24:25], v[24:25], v[48:49]
	v_lshlrev_b32_e32 v48, 16, v18
	v_and_b32_e32 v49, 0xffff0000, v18
	v_lshlrev_b32_e32 v18, 16, v22
	v_and_b32_e32 v19, 0xffff0000, v22
	v_pk_add_f32 v[18:19], v[48:49], v[18:19]
	v_mov_b32_e32 v48, v25
	v_mov_b32_e32 v49, v19
	v_mov_b32_e32 v22, v24
	v_mov_b32_e32 v23, v18
	v_pk_mul_f32 v[48:49], v[48:49], v[48:49]
	s_nop 0
	v_pk_fma_f32 v[52:53], v[22:23], v[22:23], v[48:49]
	s_waitcnt vmcnt(6)
	v_lshlrev_b32_e32 v22, 16, v14
	v_and_b32_e32 v23, 0xffff0000, v14
	v_max_f32_e32 v14, v22, v22
	v_max_f32_e32 v14, 0xc2700000, v14
	v_mul_f32_e32 v14, 0xbfb8aa3b, v14
	v_exp_f32_e32 v14, v14
	s_nop 0
	v_add_f32_e32 v14, 1.0, v14
	v_rcp_f32_e32 v48, v14
	v_max_f32_e32 v14, v23, v23
	v_max_f32_e32 v14, 0xc2700000, v14
	v_mul_f32_e32 v14, 0xbfb8aa3b, v14
	v_exp_f32_e32 v14, v14
	s_nop 0
	v_add_f32_e32 v14, 1.0, v14
	v_rcp_f32_e32 v49, v14
	s_nop 0
	v_pk_mul_f32 v[22:23], v[48:49], v[22:23]
	v_lshlrev_b32_e32 v48, 16, v17
	v_and_b32_e32 v49, 0xffff0000, v17
	v_pk_add_f32 v[48:49], v[48:49], v[50:51]
	v_lshlrev_b32_e32 v50, 16, v13
	v_and_b32_e32 v51, 0xffff0000, v13
	v_max_f32_e32 v13, v50, v50
	v_max_f32_e32 v13, 0xc2700000, v13
	v_mul_f32_e32 v13, 0xbfb8aa3b, v13
	v_exp_f32_e32 v13, v13
	v_and_b32_e32 v17, 0xffff0000, v20
	v_mov_b32_e32 v21, v48
	v_add_f32_e32 v13, 1.0, v13
	v_rcp_f32_e32 v54, v13
	v_max_f32_e32 v13, v51, v51
	v_max_f32_e32 v13, 0xc2700000, v13
	v_mul_f32_e32 v13, 0xbfb8aa3b, v13
	v_exp_f32_e32 v13, v13
	s_nop 0
	v_add_f32_e32 v13, 1.0, v13
	v_rcp_f32_e32 v55, v13
	s_nop 0
	v_pk_mul_f32 v[50:51], v[54:55], v[50:51]
	v_lshlrev_b32_e32 v54, 16, v16
	v_and_b32_e32 v55, 0xffff0000, v16
	v_lshlrev_b32_e32 v16, 16, v20
	v_pk_add_f32 v[16:17], v[54:55], v[16:17]
	v_mov_b32_e32 v55, v49
	v_mov_b32_e32 v54, v17
	v_mov_b32_e32 v20, v16
	v_pk_mul_f32 v[54:55], v[54:55], v[54:55]
	s_nop 0
	v_pk_fma_f32 v[20:21], v[20:21], v[20:21], v[54:55]
	v_lshlrev_b32_e32 v54, 16, v12
	v_and_b32_e32 v55, 0xffff0000, v12
	v_max_f32_e32 v12, v54, v54
	v_max_f32_e32 v13, v55, v55
	v_max_f32_e32 v12, 0xc2700000, v12
	v_max_f32_e32 v13, 0xc2700000, v13
	v_mul_f32_e32 v12, 0xbfb8aa3b, v12
	v_mul_f32_e32 v13, 0xbfb8aa3b, v13
	v_exp_f32_e32 v12, v12
	v_exp_f32_e32 v13, v13
	v_add_f32_e32 v12, 1.0, v12
	v_add_f32_e32 v13, 1.0, v13
	v_rcp_f32_e32 v12, v12
	v_rcp_f32_e32 v13, v13
	s_nop 0
	v_pk_mul_f32 v[12:13], v[12:13], v[54:55]
	v_mov_b32_e32 v54, v20
	v_mov_b32_e32 v55, v46
	v_mov_b32_e32 v46, v21
	v_pk_add_f32 v[20:21], v[54:55], v[46:47]
	v_mov_b32_e32 v46, v53
	v_mov_b32_e32 v47, v41
	v_pk_add_f32 v[20:21], v[46:47], v[20:21]
	v_mov_b32_e32 v53, v40
	v_pk_add_f32 v[20:21], v[52:53], v[20:21]
	ds_bpermute_b32 v41, v146, v21
	ds_bpermute_b32 v40, v146, v20
	s_waitcnt lgkmcnt(0)
	v_pk_add_f32 v[20:21], v[20:21], v[40:41]
	ds_bpermute_b32 v41, v145, v21
	ds_bpermute_b32 v40, v145, v20
	s_waitcnt lgkmcnt(0)
	v_pk_add_f32 v[20:21], v[20:21], v[40:41]
	ds_bpermute_b32 v41, v3, v21
	ds_bpermute_b32 v40, v3, v20
	s_waitcnt lgkmcnt(0)
	v_pk_add_f32 v[20:21], v[20:21], v[40:41]
	s_nop 0
	v_pk_fma_f32 v[20:21], v[20:21], s[80:81], v[84:85] op_sel_hi:[1,0,0]
	s_nop 0
	v_mul_f32_e32 v3, 0x4b800000, v21
	v_cmp_gt_f32_e64 s[38:39], s79, v21
	v_cmp_gt_f32_e32 vcc, s79, v20
	s_nop 0
	v_cndmask_b32_e64 v3, v21, v3, s[38:39]
	v_rsq_f32_e32 v3, v3
	s_nop 0
	v_mul_f32_e32 v14, 0x45800000, v3
	v_cndmask_b32_e64 v14, v3, v14, s[38:39]
	v_mul_f32_e32 v3, 0x4b800000, v20
	v_pk_mul_f32 v[28:29], v[28:29], v[14:15] op_sel_hi:[1,0]
	v_cndmask_b32_e32 v3, v20, v3, vcc
	v_pk_mul_f32 v[28:29], v[8:9], v[28:29]
	v_rsq_f32_e32 v3, v3
	v_pk_mul_f32 v[28:29], v[32:33], v[28:29]
	v_pk_mul_f32 v[32:33], v[38:39], v[14:15] op_sel_hi:[1,0]
	v_cvt_pk_bf16_f32 v28, v28, v29
	v_pk_mul_f32 v[32:33], v[10:11], v[32:33]
	v_pk_mul_f32 v[30:31], v[30:31], v[14:15] op_sel_hi:[1,0]
	v_pk_mul_f32 v[32:33], v[42:43], v[32:33]
	v_pk_mul_f32 v[30:31], v[4:5], v[30:31]
	v_cvt_pk_bf16_f32 v29, v32, v33
	v_pk_mul_f32 v[32:33], v[36:37], v[14:15] op_sel_hi:[1,0]
	v_mul_f32_e32 v14, 0x45800000, v3
	v_cndmask_b32_e32 v14, v3, v14, vcc
	v_pk_mul_f32 v[16:17], v[16:17], v[14:15] op_sel_hi:[1,0]
	v_pk_mul_f32 v[32:33], v[6:7], v[32:33]
	v_pk_mul_f32 v[8:9], v[8:9], v[16:17]
	v_pk_mul_f32 v[30:31], v[34:35], v[30:31]
	v_pk_mul_f32 v[8:9], v[12:13], v[8:9]
	v_pk_mul_f32 v[12:13], v[48:49], v[14:15] op_sel_hi:[1,0]
	v_cvt_pk_bf16_f32 v8, v8, v9
	v_pk_mul_f32 v[10:11], v[10:11], v[12:13]
	v_pk_mul_f32 v[26:27], v[26:27], v[32:33]
	v_pk_mul_f32 v[10:11], v[50:51], v[10:11]
	v_cvt_pk_bf16_f32 v30, v30, v31
	v_cvt_pk_bf16_f32 v9, v10, v11
	v_pk_mul_f32 v[10:11], v[18:19], v[14:15] op_sel_hi:[1,0]
	v_cvt_pk_bf16_f32 v31, v26, v27
	v_pk_mul_f32 v[4:5], v[4:5], v[10:11]
	v_add_co_u32_e64 v26, s[38:39], s81, v44
	v_pk_mul_f32 v[4:5], v[22:23], v[4:5]
	s_nop 0
	v_addc_co_u32_e64 v27, s[38:39], 0, v45, s[38:39]
	v_cvt_pk_bf16_f32 v10, v4, v5
	v_lshlrev_b32_e32 v4, 16, v15
	v_max_f32_e32 v3, v4, v4
	v_max_f32_e32 v3, 0xc2700000, v3
	v_mul_f32_e32 v3, 0xbfb8aa3b, v3
	v_exp_f32_e32 v3, v3
	v_and_b32_e32 v5, 0xffff0000, v15
	v_pk_mul_f32 v[14:15], v[24:25], v[14:15] op_sel_hi:[1,0]
	global_store_dwordx4 v[26:27], v[28:31], off offset:1024
	v_add_f32_e32 v3, 1.0, v3
	v_rcp_f32_e32 v12, v3
	v_max_f32_e32 v3, v5, v5
	v_max_f32_e32 v3, 0xc2700000, v3
	v_mul_f32_e32 v3, 0xbfb8aa3b, v3
	v_exp_f32_e32 v3, v3
	v_pk_mul_f32 v[6:7], v[6:7], v[14:15]
	v_add_f32_e32 v3, 1.0, v3
	v_rcp_f32_e32 v13, v3
	s_nop 0
	v_pk_mul_f32 v[4:5], v[12:13], v[4:5]
	s_nop 0
	v_pk_mul_f32 v[4:5], v[4:5], v[6:7]
	s_nop 0
	v_cvt_pk_bf16_f32 v11, v4, v5
	v_lshlrev_b64 v[4:5], 11, v[108:109]
	v_lshl_add_u64 v[4:5], s[46:47], 0, v[4:5]
	v_lshl_add_u64 v[4:5], v[4:5], 0, s[54:55]
	v_lshl_add_u64 v[0:1], v[4:5], 0, v[0:1]
	v_add_co_u32_e32 v0, vcc, 0x11000000, v0
	s_nop 1
	v_addc_co_u32_e32 v1, vcc, 0, v1, vcc
	global_store_dwordx4 v[0:1], v[8:11], off offset:1024
	s_barrier
	s_cbranch_scc0 .LBB0_684
